# adds: P7 epilogue dead zero-initialisations of DPP move destinations removed
# speedup vs baseline: 1.0149x; 1.0023x over previous
.LBB0_692:
	v_fmamk_f32 v198, v198, 0x3a800000, v215
	v_rsq_f32_e32 v198, v198
	s_cmp_lt_i32 s16, 32
	s_cselect_b32 s0, 2, 0xc2
	s_cmp_lg_u32 s16, 0
	v_pk_fma_f32 v[158:159], v[158:159], v[198:199], v[142:143] op_sel_hi:[1,0,1]
	v_pk_fma_f32 v[156:157], v[156:157], v[198:199], v[140:141] op_sel_hi:[1,0,1]
	v_pk_fma_f32 v[154:155], v[154:155], v[198:199], v[138:139] op_sel_hi:[1,0,1]
	v_pk_fma_f32 v[152:153], v[152:153], v[198:199], v[136:137] op_sel_hi:[1,0,1]
	s_cselect_b32 s46, s0, 0
	s_nop 1
	v_mov_b32_dpp v222, v156 row_ror:1 row_mask:0xf bank_mask:0xf
	v_mov_b32_dpp v226, v156 row_ror:2 row_mask:0xf bank_mask:0xf
	v_mov_b32_dpp v223, v157 row_ror:1 row_mask:0xf bank_mask:0xf
	v_mov_b32_dpp v227, v157 row_ror:2 row_mask:0xf bank_mask:0xf
	v_mov_b32_dpp v224, v158 row_ror:1 row_mask:0xf bank_mask:0xf
	v_mov_b32_dpp v228, v158 row_ror:2 row_mask:0xf bank_mask:0xf
	v_mov_b32_dpp v225, v159 row_ror:1 row_mask:0xf bank_mask:0xf
	v_mov_b32_dpp v229, v159 row_ror:2 row_mask:0xf bank_mask:0xf
	v_mov_b32_dpp v230, v152 row_ror:1 row_mask:0xf bank_mask:0xf
	v_mov_b32_dpp v233, v152 row_ror:2 row_mask:0xf bank_mask:0xf
	v_mov_b32_dpp v231, v153 row_ror:1 row_mask:0xf bank_mask:0xf
	v_mov_b32_dpp v236, v153 row_ror:2 row_mask:0xf bank_mask:0xf
	v_mov_b32_dpp v234, v154 row_ror:1 row_mask:0xf bank_mask:0xf
	v_mov_b32_dpp v239, v154 row_ror:2 row_mask:0xf bank_mask:0xf
	v_mov_b32_dpp v237, v155 row_ror:1 row_mask:0xf bank_mask:0xf
	v_mov_b32_dpp v240, v155 row_ror:2 row_mask:0xf bank_mask:0xf
	v_cmp_le_u32_e64 s[0:1], s46, v200
	s_and_saveexec_b64 s[16:17], s[0:1]
	s_cbranch_execz .LBB0_694
	v_cndmask_b32_e64 v244, v244, v239, s[8:9]
	v_cndmask_b32_e64 v245, v245, v240, s[8:9]
	v_cndmask_b32_e64 v174, v234, v174, s[6:7]
	v_cndmask_b32_e64 v175, v237, v175, s[6:7]
	s_waitcnt vmcnt(4)
	v_pk_mul_f32 v[244:245], v[126:127], v[244:245]
	v_cndmask_b32_e64 v170, v224, v170, s[6:7]
	s_waitcnt vmcnt(2)
	v_pk_fma_f32 v[174:175], v[130:131], v[174:175], v[244:245]
	v_cndmask_b32_e64 v171, v225, v171, s[6:7]
	s_waitcnt vmcnt(0)
	v_pk_fma_f32 v[154:155], v[154:155], v[134:135], v[174:175]
	v_cndmask_b32_e64 v174, v238, v228, s[8:9]
	v_cndmask_b32_e64 v175, v241, v229, s[8:9]
	v_pk_mul_f32 v[174:175], v[122:123], v[174:175]
	v_cndmask_b32_e64 v242, v242, v233, s[8:9]
	v_pk_fma_f32 v[170:171], v[114:115], v[170:171], v[174:175]
	v_cndmask_b32_e64 v243, v243, v236, s[8:9]
	v_pk_fma_f32 v[158:159], v[158:159], v[118:119], v[170:171]
	v_cndmask_b32_e64 v172, v230, v172, s[6:7]
	v_mul_f32_e32 v170, 0xbfb8aa3b, v159
	v_exp_f32_e32 v170, v170
	v_cndmask_b32_e64 v173, v231, v173, s[6:7]
	v_pk_mul_f32 v[242:243], v[124:125], v[242:243]
	v_mul_f32_e32 v171, 0xbfb8aa3b, v158
	v_add_f32_e32 v170, 1.0, v170
	v_pk_fma_f32 v[172:173], v[128:129], v[172:173], v[242:243]
	v_rcp_f32_e32 v170, v170
	v_pk_fma_f32 v[152:153], v[152:153], v[132:133], v[172:173]
	v_cndmask_b32_e64 v172, v232, v226, s[8:9]
	v_cndmask_b32_e64 v173, v235, v227, s[8:9]
	v_exp_f32_e32 v171, v171
	v_pk_mul_f32 v[172:173], v[120:121], v[172:173]
	v_cndmask_b32_e64 v168, v222, v168, s[6:7]
	v_cndmask_b32_e64 v169, v223, v169, s[6:7]
	v_pk_fma_f32 v[168:169], v[112:113], v[168:169], v[172:173]
	v_mul_f32_e32 v159, v159, v170
	v_pk_fma_f32 v[156:157], v[156:157], v[116:117], v[168:169]
	v_mul_f32_e32 v155, v159, v155
	v_add_f32_e32 v159, 1.0, v171
	v_mul_f32_e32 v168, 0xbfb8aa3b, v157
	v_mul_f32_e32 v169, 0xbfb8aa3b, v156
	v_rcp_f32_e32 v159, v159
	v_exp_f32_e32 v168, v168
	v_exp_f32_e32 v169, v169
	v_mul_f32_e32 v158, v158, v159
	v_add_f32_e32 v159, 1.0, v168
	v_add_f32_e32 v168, 1.0, v169
	v_rcp_f32_e32 v159, v159
	v_rcp_f32_e32 v168, v168
	v_mul_f32_e32 v154, v158, v154
	v_mul_f32_e32 v157, v157, v159
	v_mul_f32_e32 v156, v156, v168
	v_mul_f32_e32 v153, v157, v153
	v_mul_f32_e32 v152, v156, v152
	v_cvt_pk_bf16_f32 v152, v152, v153
	v_cvt_pk_bf16_f32 v153, v154, v155
	v_mov_b64_e32 v[154:155], s[30:31]
	v_mad_i64_i32 v[154:155], s[18:19], v194, s67, v[154:155]
	v_lshl_add_u64 v[154:155], v[192:193], 1, v[154:155]
	global_store_dwordx2 v[154:155], v[152:153], off
.LBB0_694:
	s_or_b64 exec, exec, s[16:17]
	v_fmamk_f32 v152, v221, 0x3a800000, v215
	v_rsq_f32_e32 v152, v152
	s_nop 0
	v_pk_fma_f32 v[150:151], v[150:151], v[152:153], v[142:143] op_sel_hi:[1,0,1]
	v_pk_fma_f32 v[148:149], v[148:149], v[152:153], v[140:141] op_sel_hi:[1,0,1]
	v_pk_fma_f32 v[146:147], v[146:147], v[152:153], v[138:139] op_sel_hi:[1,0,1]
	v_pk_fma_f32 v[144:145], v[144:145], v[152:153], v[136:137] op_sel_hi:[1,0,1]
	s_nop 1
	v_mov_b32_dpp v153, v148 row_ror:1 row_mask:0xf bank_mask:0xf
	v_mov_b32_dpp v158, v148 row_ror:2 row_mask:0xf bank_mask:0xf
	v_mov_b32_dpp v155, v149 row_ror:1 row_mask:0xf bank_mask:0xf
	v_mov_b32_dpp v159, v149 row_ror:2 row_mask:0xf bank_mask:0xf
	v_mov_b32_dpp v156, v150 row_ror:1 row_mask:0xf bank_mask:0xf
	v_mov_b32_dpp v168, v150 row_ror:2 row_mask:0xf bank_mask:0xf
	v_mov_b32_dpp v157, v151 row_ror:1 row_mask:0xf bank_mask:0xf
	v_mov_b32_dpp v169, v151 row_ror:2 row_mask:0xf bank_mask:0xf
	v_mov_b32_dpp v172, v144 row_ror:1 row_mask:0xf bank_mask:0xf
	v_mov_b32_dpp v174, v144 row_ror:2 row_mask:0xf bank_mask:0xf
	v_mov_b32_dpp v173, v145 row_ror:1 row_mask:0xf bank_mask:0xf
	v_mov_b32_dpp v221, v145 row_ror:2 row_mask:0xf bank_mask:0xf
	v_mov_b32_dpp v175, v146 row_ror:1 row_mask:0xf bank_mask:0xf
	v_mov_b32_dpp v235, v146 row_ror:2 row_mask:0xf bank_mask:0xf
	v_mov_b32_dpp v232, v147 row_ror:1 row_mask:0xf bank_mask:0xf
	v_mov_b32_dpp v238, v147 row_ror:2 row_mask:0xf bank_mask:0xf
	v_or_b32_e32 v203, 16, v200
	v_cmp_le_u32_e64 s[16:17], s46, v203
	v_add_u32_e32 v154, s41, v203
	s_and_saveexec_b64 s[18:19], s[16:17]
	s_cbranch_execz .LBB0_696
	v_cndmask_b32_e64 v170, v233, v174, s[8:9]
	v_cndmask_b32_e64 v171, v236, v221, s[8:9]
	v_cndmask_b32_e64 v230, v172, v230, s[6:7]
	v_cndmask_b32_e64 v231, v173, v231, s[6:7]
	s_waitcnt vmcnt(4)
	v_pk_mul_f32 v[170:171], v[124:125], v[170:171]
	v_cndmask_b32_e64 v224, v156, v224, s[6:7]
	s_waitcnt vmcnt(2)
	v_pk_fma_f32 v[170:171], v[128:129], v[230:231], v[170:171]
	v_cndmask_b32_e64 v225, v157, v225, s[6:7]
	s_waitcnt vmcnt(0)
	v_pk_fma_f32 v[144:145], v[144:145], v[132:133], v[170:171]
	v_cndmask_b32_e64 v170, v226, v158, s[8:9]
	v_cndmask_b32_e64 v171, v227, v159, s[8:9]
	v_cndmask_b32_e64 v226, v228, v168, s[8:9]
	v_cndmask_b32_e64 v227, v229, v169, s[8:9]
	v_pk_mul_f32 v[226:227], v[122:123], v[226:227]
	v_pk_mul_f32 v[170:171], v[120:121], v[170:171]
	v_pk_fma_f32 v[224:225], v[114:115], v[224:225], v[226:227]
	v_cndmask_b32_e64 v222, v153, v222, s[6:7]
	v_pk_fma_f32 v[150:151], v[150:151], v[118:119], v[224:225]
	v_cndmask_b32_e64 v223, v155, v223, s[6:7]
	v_mul_f32_e32 v208, 0xbfb8aa3b, v151
	v_exp_f32_e32 v208, v208
	v_pk_fma_f32 v[170:171], v[112:113], v[222:223], v[170:171]
	v_mul_f32_e32 v222, 0xbfb8aa3b, v150
	v_cndmask_b32_e64 v242, v239, v235, s[8:9]
	v_add_f32_e32 v208, 1.0, v208
	v_rcp_f32_e32 v208, v208
	v_cndmask_b32_e64 v243, v240, v238, s[8:9]
	v_exp_f32_e32 v222, v222
	v_cndmask_b32_e64 v236, v175, v234, s[6:7]
	v_cndmask_b32_e64 v237, v232, v237, s[6:7]
	v_pk_mul_f32 v[240:241], v[126:127], v[242:243]
	v_pk_fma_f32 v[148:149], v[148:149], v[116:117], v[170:171]
	v_pk_fma_f32 v[236:237], v[130:131], v[236:237], v[240:241]
	v_mul_f32_e32 v151, v151, v208
	v_pk_fma_f32 v[146:147], v[146:147], v[134:135], v[236:237]
	v_mul_f32_e32 v170, 0xbfb8aa3b, v149
	v_mul_f32_e32 v147, v151, v147
	v_add_f32_e32 v151, 1.0, v222
	v_mul_f32_e32 v171, 0xbfb8aa3b, v148
	v_rcp_f32_e32 v151, v151
	v_exp_f32_e32 v170, v170
	v_exp_f32_e32 v171, v171
	v_mul_f32_e32 v150, v150, v151
	v_add_f32_e32 v151, 1.0, v170
	v_add_f32_e32 v170, 1.0, v171
	v_rcp_f32_e32 v151, v151
	v_rcp_f32_e32 v170, v170
	v_mul_f32_e32 v146, v150, v146
	v_mul_f32_e32 v149, v149, v151
	v_mul_f32_e32 v148, v148, v170
	v_mul_f32_e32 v145, v149, v145
	v_mul_f32_e32 v144, v148, v144
	v_cvt_pk_bf16_f32 v144, v144, v145
	v_cvt_pk_bf16_f32 v145, v146, v147
	v_mov_b64_e32 v[146:147], s[30:31]
	v_mad_i64_i32 v[146:147], s[20:21], v154, s67, v[146:147]
	v_lshl_add_u64 v[146:147], v[192:193], 1, v[146:147]
	global_store_dwordx2 v[146:147], v[144:145], off
.LBB0_696:
	s_or_b64 exec, exec, s[18:19]
	v_fmamk_f32 v144, v220, 0x3a800000, v215
	v_rsq_f32_e32 v144, v144
	s_nop 0
	v_pk_fma_f32 v[110:111], v[110:111], v[144:145], v[142:143] op_sel_hi:[1,0,1]
	v_pk_fma_f32 v[108:109], v[108:109], v[144:145], v[140:141] op_sel_hi:[1,0,1]
	v_pk_fma_f32 v[102:103], v[102:103], v[144:145], v[138:139] op_sel_hi:[1,0,1]
	v_pk_fma_f32 v[100:101], v[100:101], v[144:145], v[136:137] op_sel_hi:[1,0,1]
	s_nop 1
	v_mov_b32_dpp v145, v108 row_ror:1 row_mask:0xf bank_mask:0xf
	v_mov_b32_dpp v150, v108 row_ror:2 row_mask:0xf bank_mask:0xf
	v_mov_b32_dpp v146, v109 row_ror:1 row_mask:0xf bank_mask:0xf
	v_mov_b32_dpp v151, v109 row_ror:2 row_mask:0xf bank_mask:0xf
	v_mov_b32_dpp v148, v110 row_ror:1 row_mask:0xf bank_mask:0xf
	v_mov_b32_dpp v170, v110 row_ror:2 row_mask:0xf bank_mask:0xf
	v_mov_b32_dpp v149, v111 row_ror:1 row_mask:0xf bank_mask:0xf
	v_mov_b32_dpp v171, v111 row_ror:2 row_mask:0xf bank_mask:0xf
	v_mov_b32_dpp v220, v100 row_ror:1 row_mask:0xf bank_mask:0xf
	v_mov_b32_dpp v223, v100 row_ror:2 row_mask:0xf bank_mask:0xf
	v_mov_b32_dpp v222, v101 row_ror:1 row_mask:0xf bank_mask:0xf
	v_mov_b32_dpp v225, v101 row_ror:2 row_mask:0xf bank_mask:0xf
	v_mov_b32_dpp v224, v102 row_ror:1 row_mask:0xf bank_mask:0xf
	v_mov_b32_dpp v227, v102 row_ror:2 row_mask:0xf bank_mask:0xf
	v_mov_b32_dpp v226, v103 row_ror:1 row_mask:0xf bank_mask:0xf
	v_mov_b32_dpp v228, v103 row_ror:2 row_mask:0xf bank_mask:0xf
	v_or_b32_e32 v204, 32, v200
	v_cmp_le_u32_e64 s[18:19], s46, v204
	v_add_u32_e32 v147, s41, v204
	s_and_saveexec_b64 s[20:21], s[18:19]
	s_cbranch_execz .LBB0_698
	v_cndmask_b32_e64 v168, v168, v170, s[8:9]
	v_cndmask_b32_e64 v169, v169, v171, s[8:9]
	s_waitcnt vmcnt(5)
	v_pk_mul_f32 v[168:169], v[122:123], v[168:169]
	v_cndmask_b32_e64 v156, v148, v156, s[6:7]
	v_cndmask_b32_e64 v157, v149, v157, s[6:7]
	s_waitcnt vmcnt(3)
	v_pk_fma_f32 v[156:157], v[114:115], v[156:157], v[168:169]
	v_cndmask_b32_e64 v234, v235, v227, s[8:9]
	s_waitcnt vmcnt(1)
	v_pk_fma_f32 v[110:111], v[110:111], v[118:119], v[156:157]
	v_cndmask_b32_e64 v157, v146, v155, s[6:7]
	v_mul_f32_e32 v156, 0xbfb8aa3b, v111
	v_exp_f32_e32 v168, v156
	v_cndmask_b32_e64 v156, v145, v153, s[6:7]
	v_mul_f32_e32 v155, 0xbfb8aa3b, v110
	v_cndmask_b32_e64 v235, v238, v228, s[8:9]
	v_add_f32_e32 v153, 1.0, v168
	v_rcp_f32_e32 v153, v153
	v_cndmask_b32_e64 v158, v158, v150, s[8:9]
	v_cndmask_b32_e64 v159, v159, v151, s[8:9]
	v_exp_f32_e32 v155, v155
	v_cndmask_b32_e64 v230, v174, v223, s[8:9]
	v_cndmask_b32_e64 v174, v224, v175, s[6:7]
	v_cndmask_b32_e64 v175, v226, v232, s[6:7]
	v_pk_mul_f32 v[232:233], v[126:127], v[234:235]
	v_pk_mul_f32 v[158:159], v[120:121], v[158:159]
	v_pk_fma_f32 v[174:175], v[130:131], v[174:175], v[232:233]
	v_pk_fma_f32 v[156:157], v[112:113], v[156:157], v[158:159]
	s_waitcnt vmcnt(0)
	v_pk_fma_f32 v[102:103], v[102:103], v[134:135], v[174:175]
	v_pk_fma_f32 v[108:109], v[108:109], v[116:117], v[156:157]
	v_mul_f32_e32 v111, v111, v153
	v_mul_f32_e32 v103, v111, v103
	v_add_f32_e32 v111, 1.0, v155
	v_mul_f32_e32 v153, 0xbfb8aa3b, v109
	v_mul_f32_e32 v155, 0xbfb8aa3b, v108
	v_rcp_f32_e32 v111, v111
	v_exp_f32_e32 v153, v153
	v_exp_f32_e32 v155, v155
	v_cndmask_b32_e64 v231, v221, v225, s[8:9]
	v_mul_f32_e32 v110, v110, v111
	v_add_f32_e32 v111, 1.0, v153
	v_add_f32_e32 v153, 1.0, v155
	v_rcp_f32_e32 v111, v111
	v_rcp_f32_e32 v153, v153
	v_cndmask_b32_e64 v172, v220, v172, s[6:7]
	v_cndmask_b32_e64 v173, v222, v173, s[6:7]
	v_pk_mul_f32 v[230:231], v[124:125], v[230:231]
	v_mul_f32_e32 v109, v109, v111
	v_pk_fma_f32 v[172:173], v[128:129], v[172:173], v[230:231]
	v_mul_f32_e32 v108, v108, v153
	v_pk_fma_f32 v[100:101], v[100:101], v[132:133], v[172:173]
	v_mul_f32_e32 v102, v110, v102
	v_mul_f32_e32 v101, v109, v101
	v_mul_f32_e32 v100, v108, v100
	v_cvt_pk_bf16_f32 v100, v100, v101
	v_cvt_pk_bf16_f32 v101, v102, v103
	v_mov_b64_e32 v[102:103], s[30:31]
	v_mad_i64_i32 v[102:103], s[22:23], v147, s67, v[102:103]
	v_lshl_add_u64 v[102:103], v[192:193], 1, v[102:103]
	global_store_dwordx2 v[102:103], v[100:101], off
.LBB0_698:
	s_or_b64 exec, exec, s[20:21]
	s_nop 1
	v_mov_b32_dpp v100, v160 row_ror:1 row_mask:0xf bank_mask:0xf
	v_mov_b32_dpp v108, v160 row_ror:2 row_mask:0xf bank_mask:0xf
	v_mov_b32_dpp v101, v161 row_ror:1 row_mask:0xf bank_mask:0xf
	v_mov_b32_dpp v110, v161 row_ror:2 row_mask:0xf bank_mask:0xf
	v_mov_b32_dpp v102, v162 row_ror:1 row_mask:0xf bank_mask:0xf
	v_mov_b32_dpp v111, v162 row_ror:2 row_mask:0xf bank_mask:0xf
	v_mov_b32_dpp v103, v163 row_ror:1 row_mask:0xf bank_mask:0xf
	v_mov_b32_dpp v153, v163 row_ror:2 row_mask:0xf bank_mask:0xf
	v_mov_b32_dpp v155, v164 row_ror:1 row_mask:0xf bank_mask:0xf
	v_mov_b32_dpp v157, v164 row_ror:2 row_mask:0xf bank_mask:0xf
	v_mov_b32_dpp v156, v165 row_ror:1 row_mask:0xf bank_mask:0xf
	v_mov_b32_dpp v159, v165 row_ror:2 row_mask:0xf bank_mask:0xf
	v_mov_b32_dpp v158, v166 row_ror:1 row_mask:0xf bank_mask:0xf
	v_mov_b32_dpp v169, v166 row_ror:2 row_mask:0xf bank_mask:0xf
	v_mov_b32_dpp v168, v167 row_ror:1 row_mask:0xf bank_mask:0xf
	v_mov_b32_dpp v172, v167 row_ror:2 row_mask:0xf bank_mask:0xf
	v_or_b32_e32 v205, 48, v200
	v_cmp_le_u32_e64 s[20:21], s46, v205
	v_add_u32_e32 v109, s41, v205
	s_and_saveexec_b64 s[22:23], s[20:21]
	s_cbranch_execz .LBB0_700
	v_cndmask_b32_e64 v151, v151, v110, s[8:9]
	v_cndmask_b32_e64 v110, v170, v111, s[8:9]
	v_cndmask_b32_e64 v111, v171, v153, s[8:9]
	s_waitcnt vmcnt(5)
	v_pk_mul_f32 v[110:111], v[122:123], v[110:111]
	v_cndmask_b32_e64 v102, v102, v148, s[6:7]
	v_cndmask_b32_e64 v103, v103, v149, s[6:7]
	s_waitcnt vmcnt(3)
	v_pk_fma_f32 v[102:103], v[114:115], v[102:103], v[110:111]
	v_cndmask_b32_e64 v150, v150, v108, s[8:9]
	s_waitcnt vmcnt(1)
	v_pk_fma_f32 v[102:103], v[162:163], v[118:119], v[102:103]
	v_pk_mul_f32 v[150:151], v[120:121], v[150:151]
	v_mul_f32_e32 v108, 0xbfb8aa3b, v103
	v_exp_f32_e32 v108, v108
	v_mul_f32_e32 v110, 0xbfb8aa3b, v102
	v_exp_f32_e32 v110, v110
	v_cndmask_b32_e64 v100, v100, v145, s[6:7]
	v_add_f32_e32 v108, 1.0, v108
	v_rcp_f32_e32 v108, v108
	v_cndmask_b32_e64 v101, v101, v146, s[6:7]
	v_pk_fma_f32 v[100:101], v[112:113], v[100:101], v[150:151]
	v_cndmask_b32_e64 v174, v223, v157, s[8:9]
	v_pk_fma_f32 v[100:101], v[160:161], v[116:117], v[100:101]
	v_mul_f32_e32 v103, v103, v108
	v_add_f32_e32 v108, 1.0, v110
	v_mul_f32_e32 v110, 0xbfb8aa3b, v101
	v_mul_f32_e32 v111, 0xbfb8aa3b, v100
	v_rcp_f32_e32 v108, v108
	v_exp_f32_e32 v110, v110
	v_exp_f32_e32 v111, v111
	v_cndmask_b32_e64 v175, v225, v159, s[8:9]
	v_mul_f32_e32 v102, v102, v108
	v_add_f32_e32 v108, 1.0, v110
	v_add_f32_e32 v110, 1.0, v111
	v_rcp_f32_e32 v108, v108
	v_rcp_f32_e32 v110, v110
	v_cndmask_b32_e64 v230, v227, v169, s[8:9]
	v_cndmask_b32_e64 v231, v228, v172, s[8:9]
	v_cndmask_b32_e64 v172, v155, v220, s[6:7]
	v_cndmask_b32_e64 v173, v156, v222, s[6:7]
	v_cndmask_b32_e64 v156, v158, v224, s[6:7]
	v_cndmask_b32_e64 v157, v168, v226, s[6:7]
	v_pk_mul_f32 v[158:159], v[124:125], v[174:175]
	v_pk_mul_f32 v[168:169], v[126:127], v[230:231]
	v_pk_fma_f32 v[158:159], v[128:129], v[172:173], v[158:159]
	v_pk_fma_f32 v[156:157], v[130:131], v[156:157], v[168:169]
	s_waitcnt vmcnt(0)
	v_pk_fma_f32 v[158:159], v[164:165], v[132:133], v[158:159]
	v_pk_fma_f32 v[156:157], v[166:167], v[134:135], v[156:157]
	v_mul_f32_e32 v101, v101, v108
	v_mul_f32_e32 v100, v100, v110
	v_mul_f32_e32 v103, v103, v157
	v_mul_f32_e32 v102, v102, v156
	v_mul_f32_e32 v101, v101, v159
	v_mul_f32_e32 v100, v100, v158
	v_cvt_pk_bf16_f32 v100, v100, v101
	v_cvt_pk_bf16_f32 v101, v102, v103
	v_mov_b64_e32 v[102:103], s[30:31]
	v_mad_i64_i32 v[102:103], s[24:25], v109, s67, v[102:103]
	v_lshl_add_u64 v[102:103], v[192:193], 1, v[102:103]
	global_store_dwordx2 v[102:103], v[100:101], off
.LBB0_700:
	s_or_b64 exec, exec, s[22:23]
	v_fmamk_f32 v100, v219, 0x3a800000, v215
	v_rsq_f32_e32 v108, v100
	s_nop 0
	v_pk_fma_f32 v[94:95], v[94:95], v[108:109], v[142:143] op_sel_hi:[1,0,1]
	v_pk_fma_f32 v[92:93], v[92:93], v[108:109], v[140:141] op_sel_hi:[1,0,1]
	v_pk_fma_f32 v[90:91], v[90:91], v[108:109], v[138:139] op_sel_hi:[1,0,1]
	v_pk_fma_f32 v[88:89], v[88:89], v[108:109], v[136:137] op_sel_hi:[1,0,1]
	s_nop 1
	v_mov_b32_dpp v100, v92 row_ror:1 row_mask:0xf bank_mask:0xf
	v_mov_b32_dpp v110, v92 row_ror:2 row_mask:0xf bank_mask:0xf
	v_mov_b32_dpp v101, v93 row_ror:1 row_mask:0xf bank_mask:0xf
	v_mov_b32_dpp v145, v93 row_ror:2 row_mask:0xf bank_mask:0xf
	v_mov_b32_dpp v102, v94 row_ror:1 row_mask:0xf bank_mask:0xf
	v_mov_b32_dpp v150, v94 row_ror:2 row_mask:0xf bank_mask:0xf
	v_mov_b32_dpp v103, v95 row_ror:1 row_mask:0xf bank_mask:0xf
	v_mov_b32_dpp v151, v95 row_ror:2 row_mask:0xf bank_mask:0xf
	v_mov_b32_dpp v153, v88 row_ror:1 row_mask:0xf bank_mask:0xf
	v_mov_b32_dpp v156, v88 row_ror:2 row_mask:0xf bank_mask:0xf
	v_mov_b32_dpp v155, v89 row_ror:1 row_mask:0xf bank_mask:0xf
	v_mov_b32_dpp v158, v89 row_ror:2 row_mask:0xf bank_mask:0xf
	v_mov_b32_dpp v157, v90 row_ror:1 row_mask:0xf bank_mask:0xf
	v_mov_b32_dpp v160, v90 row_ror:2 row_mask:0xf bank_mask:0xf
	v_mov_b32_dpp v159, v91 row_ror:1 row_mask:0xf bank_mask:0xf
	v_mov_b32_dpp v161, v91 row_ror:2 row_mask:0xf bank_mask:0xf
	v_add_u32_e32 v206, 0x80, v200
	v_cmp_le_u32_e64 s[22:23], s46, v206
	v_add_u32_e32 v149, s64, v202
	v_add_u32_e32 v111, s41, v206
	s_and_saveexec_b64 s[24:25], s[22:23]
	s_cbranch_execz .LBB0_702
	ds_read_b128 v[162:165], v149 offset:288
	ds_read_b128 v[166:169], v149 offset:32
	ds_read_b128 v[170:173], v149
	ds_read_b128 v[220:223], v149 offset:256
	s_waitcnt lgkmcnt(2)
	v_cndmask_b32_e64 v146, v165, v169, s[6:7]
	v_cndmask_b32_e64 v148, v164, v168, s[6:7]
	v_cndmask_b32_e64 v168, v148, v160, s[8:9]
	v_cndmask_b32_e64 v169, v146, v161, s[8:9]
	v_cndmask_b32_e64 v167, v163, v167, s[6:7]
	v_cndmask_b32_e64 v166, v162, v166, s[6:7]
	v_cndmask_b32_e64 v164, v157, v164, s[6:7]
	v_cndmask_b32_e64 v165, v159, v165, s[6:7]
	s_waitcnt vmcnt(4)
	v_pk_mul_f32 v[168:169], v[126:127], v[168:169]
	v_cndmask_b32_e64 v166, v166, v156, s[8:9]
	v_cndmask_b32_e64 v167, v167, v158, s[8:9]
	s_waitcnt vmcnt(2)
	v_pk_fma_f32 v[164:165], v[130:131], v[164:165], v[168:169]
	s_waitcnt lgkmcnt(0)
	v_cndmask_b32_e64 v146, v223, v173, s[6:7]
	v_cndmask_b32_e64 v148, v222, v172, s[6:7]
	v_cndmask_b32_e64 v162, v153, v162, s[6:7]
	v_cndmask_b32_e64 v163, v155, v163, s[6:7]
	v_pk_mul_f32 v[166:167], v[124:125], v[166:167]
	s_waitcnt vmcnt(0)
	v_pk_fma_f32 v[90:91], v[90:91], v[134:135], v[164:165]
	v_cndmask_b32_e64 v164, v148, v150, s[8:9]
	v_cndmask_b32_e64 v165, v146, v151, s[8:9]
	v_pk_fma_f32 v[162:163], v[128:129], v[162:163], v[166:167]
	v_pk_mul_f32 v[164:165], v[122:123], v[164:165]
	v_cndmask_b32_e64 v166, v102, v222, s[6:7]
	v_cndmask_b32_e64 v167, v103, v223, s[6:7]
	v_pk_fma_f32 v[164:165], v[114:115], v[166:167], v[164:165]
	v_pk_fma_f32 v[88:89], v[88:89], v[132:133], v[162:163]
	v_pk_fma_f32 v[94:95], v[94:95], v[118:119], v[164:165]
	v_cndmask_b32_e64 v163, v221, v171, s[6:7]
	v_mul_f32_e32 v146, 0xbfb8aa3b, v95
	v_exp_f32_e32 v146, v146
	v_cndmask_b32_e64 v162, v220, v170, s[6:7]
	v_mul_f32_e32 v148, 0xbfb8aa3b, v94
	v_cndmask_b32_e64 v162, v162, v110, s[8:9]
	v_add_f32_e32 v146, 1.0, v146
	v_rcp_f32_e32 v146, v146
	v_cndmask_b32_e64 v163, v163, v145, s[8:9]
	v_exp_f32_e32 v148, v148
	v_pk_mul_f32 v[162:163], v[120:121], v[162:163]
	v_cndmask_b32_e64 v164, v100, v220, s[6:7]
	v_cndmask_b32_e64 v165, v101, v221, s[6:7]
	v_pk_fma_f32 v[162:163], v[112:113], v[164:165], v[162:163]
	v_mul_f32_e32 v95, v95, v146
	v_pk_fma_f32 v[92:93], v[92:93], v[116:117], v[162:163]
	v_mul_f32_e32 v91, v91, v95
	v_add_f32_e32 v95, 1.0, v148
	v_mul_f32_e32 v146, 0xbfb8aa3b, v93
	v_mul_f32_e32 v148, 0xbfb8aa3b, v92
	v_rcp_f32_e32 v95, v95
	v_exp_f32_e32 v146, v146
	v_exp_f32_e32 v148, v148
	v_mul_f32_e32 v94, v94, v95
	v_add_f32_e32 v95, 1.0, v146
	v_add_f32_e32 v146, 1.0, v148
	v_rcp_f32_e32 v95, v95
	v_rcp_f32_e32 v146, v146
	v_mul_f32_e32 v90, v90, v94
	v_mul_f32_e32 v93, v93, v95
	v_mul_f32_e32 v92, v92, v146
	v_mul_f32_e32 v89, v89, v93
	v_mul_f32_e32 v88, v88, v92
	v_cvt_pk_bf16_f32 v88, v88, v89
	v_cvt_pk_bf16_f32 v89, v90, v91
	v_mov_b64_e32 v[90:91], s[30:31]
	v_mad_i64_i32 v[90:91], s[26:27], v111, s67, v[90:91]
	v_lshl_add_u64 v[90:91], v[192:193], 1, v[90:91]
	global_store_dwordx2 v[90:91], v[88:89], off
.LBB0_702:
	s_or_b64 exec, exec, s[24:25]
	v_fmamk_f32 v88, v218, 0x3a800000, v215
	v_rsq_f32_e32 v146, v88
	s_nop 0
	v_pk_fma_f32 v[86:87], v[86:87], v[146:147], v[142:143] op_sel_hi:[1,0,1]
	v_pk_fma_f32 v[84:85], v[84:85], v[146:147], v[140:141] op_sel_hi:[1,0,1]
	v_pk_fma_f32 v[82:83], v[82:83], v[146:147], v[138:139] op_sel_hi:[1,0,1]
	v_pk_fma_f32 v[80:81], v[80:81], v[146:147], v[136:137] op_sel_hi:[1,0,1]
	s_nop 1
	v_mov_b32_dpp v88, v84 row_ror:1 row_mask:0xf bank_mask:0xf
	v_mov_b32_dpp v92, v84 row_ror:2 row_mask:0xf bank_mask:0xf
	v_mov_b32_dpp v89, v85 row_ror:1 row_mask:0xf bank_mask:0xf
	v_mov_b32_dpp v93, v85 row_ror:2 row_mask:0xf bank_mask:0xf
	v_mov_b32_dpp v90, v86 row_ror:1 row_mask:0xf bank_mask:0xf
	v_mov_b32_dpp v94, v86 row_ror:2 row_mask:0xf bank_mask:0xf
	v_mov_b32_dpp v91, v87 row_ror:1 row_mask:0xf bank_mask:0xf
	v_mov_b32_dpp v95, v87 row_ror:2 row_mask:0xf bank_mask:0xf
	v_mov_b32_dpp v162, v80 row_ror:1 row_mask:0xf bank_mask:0xf
	v_mov_b32_dpp v164, v80 row_ror:2 row_mask:0xf bank_mask:0xf
	v_mov_b32_dpp v163, v81 row_ror:1 row_mask:0xf bank_mask:0xf
	v_mov_b32_dpp v166, v81 row_ror:2 row_mask:0xf bank_mask:0xf
	v_mov_b32_dpp v165, v82 row_ror:1 row_mask:0xf bank_mask:0xf
	v_mov_b32_dpp v168, v82 row_ror:2 row_mask:0xf bank_mask:0xf
	v_mov_b32_dpp v167, v83 row_ror:1 row_mask:0xf bank_mask:0xf
	v_mov_b32_dpp v169, v83 row_ror:2 row_mask:0xf bank_mask:0xf
	v_add_u32_e32 v207, 0x90, v200
	v_cmp_le_u32_e64 s[24:25], s46, v207
	v_add_u32_e32 v148, s41, v207
	s_and_saveexec_b64 s[26:27], s[24:25]
	s_cbranch_execz .LBB0_704
	v_cndmask_b32_e64 v150, v150, v94, s[8:9]
	v_cndmask_b32_e64 v151, v151, v95, s[8:9]
	s_waitcnt vmcnt(5)
	v_pk_mul_f32 v[150:151], v[122:123], v[150:151]
	v_cndmask_b32_e64 v102, v90, v102, s[6:7]
	v_cndmask_b32_e64 v103, v91, v103, s[6:7]
	s_waitcnt vmcnt(3)
	v_pk_fma_f32 v[102:103], v[114:115], v[102:103], v[150:151]
	v_cndmask_b32_e64 v160, v160, v168, s[8:9]
	s_waitcnt vmcnt(1)
	v_pk_fma_f32 v[86:87], v[86:87], v[118:119], v[102:103]
	v_cndmask_b32_e64 v161, v161, v169, s[8:9]
	v_mul_f32_e32 v102, 0xbfb8aa3b, v87
	v_exp_f32_e32 v102, v102
	v_cndmask_b32_e64 v170, v156, v164, s[8:9]
	v_cndmask_b32_e64 v156, v165, v157, s[6:7]
	v_cndmask_b32_e64 v157, v167, v159, s[6:7]
	v_pk_mul_f32 v[160:161], v[126:127], v[160:161]
	v_add_f32_e32 v102, 1.0, v102
	v_pk_fma_f32 v[156:157], v[130:131], v[156:157], v[160:161]
	v_rcp_f32_e32 v102, v102
	v_mul_f32_e32 v103, 0xbfb8aa3b, v86
	s_waitcnt vmcnt(0)
	v_pk_fma_f32 v[82:83], v[82:83], v[134:135], v[156:157]
	v_cndmask_b32_e64 v156, v110, v92, s[8:9]
	v_cndmask_b32_e64 v157, v145, v93, s[8:9]
	v_exp_f32_e32 v103, v103
	v_pk_mul_f32 v[156:157], v[120:121], v[156:157]
	v_cndmask_b32_e64 v100, v88, v100, s[6:7]
	v_cndmask_b32_e64 v101, v89, v101, s[6:7]
	v_pk_fma_f32 v[100:101], v[112:113], v[100:101], v[156:157]
	v_mul_f32_e32 v87, v87, v102
	v_pk_fma_f32 v[84:85], v[84:85], v[116:117], v[100:101]
	v_mul_f32_e32 v83, v87, v83
	v_add_f32_e32 v87, 1.0, v103
	v_mul_f32_e32 v100, 0xbfb8aa3b, v85
	v_mul_f32_e32 v101, 0xbfb8aa3b, v84
	v_rcp_f32_e32 v87, v87
	v_exp_f32_e32 v100, v100
	v_exp_f32_e32 v101, v101
	v_cndmask_b32_e64 v171, v158, v166, s[8:9]
	v_mul_f32_e32 v86, v86, v87
	v_add_f32_e32 v87, 1.0, v100
	v_add_f32_e32 v100, 1.0, v101
	v_rcp_f32_e32 v87, v87
	v_rcp_f32_e32 v100, v100
	v_cndmask_b32_e64 v172, v162, v153, s[6:7]
	v_cndmask_b32_e64 v173, v163, v155, s[6:7]
	v_pk_mul_f32 v[158:159], v[124:125], v[170:171]
	v_mul_f32_e32 v85, v85, v87
	v_pk_fma_f32 v[158:159], v[128:129], v[172:173], v[158:159]
	v_mul_f32_e32 v84, v84, v100
	v_pk_fma_f32 v[80:81], v[80:81], v[132:133], v[158:159]
	v_mul_f32_e32 v82, v86, v82
	v_mul_f32_e32 v81, v85, v81
	v_mul_f32_e32 v80, v84, v80
	v_cvt_pk_bf16_f32 v80, v80, v81
	v_cvt_pk_bf16_f32 v81, v82, v83
	v_mov_b64_e32 v[82:83], s[30:31]
	v_mad_i64_i32 v[82:83], s[28:29], v148, s67, v[82:83]
	v_lshl_add_u64 v[82:83], v[192:193], 1, v[82:83]
	global_store_dwordx2 v[82:83], v[80:81], off
.LBB0_704:
	s_or_b64 exec, exec, s[26:27]
	v_fmamk_f32 v80, v199, 0x3a800000, v215
	v_rsq_f32_e32 v110, v80
	s_nop 0
	v_pk_fma_f32 v[78:79], v[78:79], v[110:111], v[142:143] op_sel_hi:[1,0,1]
	v_pk_fma_f32 v[76:77], v[76:77], v[110:111], v[140:141] op_sel_hi:[1,0,1]
	v_pk_fma_f32 v[74:75], v[74:75], v[110:111], v[138:139] op_sel_hi:[1,0,1]
	v_pk_fma_f32 v[72:73], v[72:73], v[110:111], v[136:137] op_sel_hi:[1,0,1]
	s_nop 1
	v_mov_b32_dpp v80, v76 row_ror:1 row_mask:0xf bank_mask:0xf
	v_mov_b32_dpp v84, v76 row_ror:2 row_mask:0xf bank_mask:0xf
	v_mov_b32_dpp v81, v77 row_ror:1 row_mask:0xf bank_mask:0xf
	v_mov_b32_dpp v85, v77 row_ror:2 row_mask:0xf bank_mask:0xf
	v_mov_b32_dpp v82, v78 row_ror:1 row_mask:0xf bank_mask:0xf
	v_mov_b32_dpp v86, v78 row_ror:2 row_mask:0xf bank_mask:0xf
	v_mov_b32_dpp v83, v79 row_ror:1 row_mask:0xf bank_mask:0xf
	v_mov_b32_dpp v87, v79 row_ror:2 row_mask:0xf bank_mask:0xf
	v_mov_b32_dpp v100, v72 row_ror:1 row_mask:0xf bank_mask:0xf
	v_mov_b32_dpp v102, v72 row_ror:2 row_mask:0xf bank_mask:0xf
	v_mov_b32_dpp v101, v73 row_ror:1 row_mask:0xf bank_mask:0xf
	v_mov_b32_dpp v138, v73 row_ror:2 row_mask:0xf bank_mask:0xf
	v_mov_b32_dpp v103, v74 row_ror:1 row_mask:0xf bank_mask:0xf
	v_mov_b32_dpp v140, v74 row_ror:2 row_mask:0xf bank_mask:0xf
	v_mov_b32_dpp v139, v75 row_ror:1 row_mask:0xf bank_mask:0xf
	v_mov_b32_dpp v141, v75 row_ror:2 row_mask:0xf bank_mask:0xf
	v_add_u32_e32 v209, 0xa0, v200
	v_cmp_le_u32_e64 s[26:27], s46, v209
	v_add_u32_e32 v136, s41, v209
	s_and_saveexec_b64 s[28:29], s[26:27]
	s_cbranch_execz .LBB0_706
	v_cndmask_b32_e64 v94, v94, v86, s[8:9]
	v_cndmask_b32_e64 v95, v95, v87, s[8:9]
	s_waitcnt vmcnt(5)
	v_pk_mul_f32 v[94:95], v[122:123], v[94:95]
	v_cndmask_b32_e64 v90, v82, v90, s[6:7]
	v_cndmask_b32_e64 v91, v83, v91, s[6:7]
	s_waitcnt vmcnt(3)
	v_pk_fma_f32 v[90:91], v[114:115], v[90:91], v[94:95]
	v_cndmask_b32_e64 v150, v168, v140, s[8:9]
	s_waitcnt vmcnt(1)
	v_pk_fma_f32 v[78:79], v[78:79], v[118:119], v[90:91]
	v_cndmask_b32_e64 v151, v169, v141, s[8:9]
	v_mul_f32_e32 v90, 0xbfb8aa3b, v79
	v_exp_f32_e32 v90, v90
	v_mul_f32_e32 v91, 0xbfb8aa3b, v78
	v_cndmask_b32_e64 v92, v92, v84, s[8:9]
	v_cndmask_b32_e64 v93, v93, v85, s[8:9]
	v_add_f32_e32 v90, 1.0, v90
	v_rcp_f32_e32 v90, v90
	v_exp_f32_e32 v91, v91
	v_cndmask_b32_e64 v158, v103, v165, s[6:7]
	v_cndmask_b32_e64 v159, v139, v167, s[6:7]
	v_pk_mul_f32 v[150:151], v[126:127], v[150:151]
	v_pk_mul_f32 v[92:93], v[120:121], v[92:93]
	v_cndmask_b32_e64 v88, v80, v88, s[6:7]
	v_cndmask_b32_e64 v89, v81, v89, s[6:7]
	v_pk_fma_f32 v[150:151], v[130:131], v[158:159], v[150:151]
	v_pk_fma_f32 v[88:89], v[112:113], v[88:89], v[92:93]
	s_waitcnt vmcnt(0)
	v_pk_fma_f32 v[74:75], v[74:75], v[134:135], v[150:151]
	v_pk_fma_f32 v[76:77], v[76:77], v[116:117], v[88:89]
	v_mul_f32_e32 v79, v79, v90
	v_mul_f32_e32 v75, v79, v75
	v_add_f32_e32 v79, 1.0, v91
	v_mul_f32_e32 v88, 0xbfb8aa3b, v77
	v_mul_f32_e32 v89, 0xbfb8aa3b, v76
	v_rcp_f32_e32 v79, v79
	v_exp_f32_e32 v88, v88
	v_exp_f32_e32 v89, v89
	v_cndmask_b32_e64 v142, v164, v102, s[8:9]
	v_mul_f32_e32 v78, v78, v79
	v_add_f32_e32 v79, 1.0, v88
	v_add_f32_e32 v88, 1.0, v89
	v_rcp_f32_e32 v79, v79
	v_rcp_f32_e32 v88, v88
	v_cndmask_b32_e64 v143, v166, v138, s[8:9]
	v_cndmask_b32_e64 v156, v100, v162, s[6:7]
	v_cndmask_b32_e64 v157, v101, v163, s[6:7]
	v_pk_mul_f32 v[142:143], v[124:125], v[142:143]
	v_mul_f32_e32 v77, v77, v79
	v_pk_fma_f32 v[142:143], v[128:129], v[156:157], v[142:143]
	v_mul_f32_e32 v76, v76, v88
	v_pk_fma_f32 v[72:73], v[72:73], v[132:133], v[142:143]
	v_mul_f32_e32 v74, v78, v74
	v_mul_f32_e32 v73, v77, v73
	v_mul_f32_e32 v72, v76, v72
	v_cvt_pk_bf16_f32 v72, v72, v73
	v_cvt_pk_bf16_f32 v73, v74, v75
	v_mov_b64_e32 v[74:75], s[30:31]
	v_mad_i64_i32 v[74:75], s[70:71], v136, s67, v[74:75]
	v_lshl_add_u64 v[74:75], v[192:193], 1, v[74:75]
	global_store_dwordx2 v[74:75], v[72:73], off
.LBB0_706:
	s_or_b64 exec, exec, s[28:29]
	s_nop 1
	v_mov_b32_dpp v72, v96 row_ror:1 row_mask:0xf bank_mask:0xf
	v_mov_b32_dpp v76, v96 row_ror:2 row_mask:0xf bank_mask:0xf
	v_mov_b32_dpp v73, v97 row_ror:1 row_mask:0xf bank_mask:0xf
	v_mov_b32_dpp v77, v97 row_ror:2 row_mask:0xf bank_mask:0xf
	v_mov_b32_dpp v74, v98 row_ror:1 row_mask:0xf bank_mask:0xf
	v_mov_b32_dpp v78, v98 row_ror:2 row_mask:0xf bank_mask:0xf
	v_mov_b32_dpp v75, v99 row_ror:1 row_mask:0xf bank_mask:0xf
	v_mov_b32_dpp v79, v99 row_ror:2 row_mask:0xf bank_mask:0xf
	v_mov_b32_dpp v88, v104 row_ror:1 row_mask:0xf bank_mask:0xf
	v_mov_b32_dpp v90, v104 row_ror:2 row_mask:0xf bank_mask:0xf
	v_mov_b32_dpp v89, v105 row_ror:1 row_mask:0xf bank_mask:0xf
	v_mov_b32_dpp v92, v105 row_ror:2 row_mask:0xf bank_mask:0xf
	v_mov_b32_dpp v91, v106 row_ror:1 row_mask:0xf bank_mask:0xf
	v_mov_b32_dpp v94, v106 row_ror:2 row_mask:0xf bank_mask:0xf
	v_mov_b32_dpp v93, v107 row_ror:1 row_mask:0xf bank_mask:0xf
	v_mov_b32_dpp v95, v107 row_ror:2 row_mask:0xf bank_mask:0xf
	v_add_u32_e32 v210, 0xb0, v200
	v_cmp_le_u32_e64 s[28:29], s46, v210
	v_add_u32_e32 v137, s41, v210
	s_and_saveexec_b64 s[46:47], s[28:29]
	s_cbranch_execz .LBB0_708
	v_cndmask_b32_e64 v78, v86, v78, s[8:9]
	v_cndmask_b32_e64 v79, v87, v79, s[8:9]
	s_waitcnt vmcnt(5)
	v_pk_mul_f32 v[78:79], v[122:123], v[78:79]
	v_cndmask_b32_e64 v74, v74, v82, s[6:7]
	v_cndmask_b32_e64 v75, v75, v83, s[6:7]
	s_waitcnt vmcnt(3)
	v_pk_fma_f32 v[74:75], v[114:115], v[74:75], v[78:79]
	v_cndmask_b32_e64 v76, v84, v76, s[8:9]
	s_waitcnt vmcnt(1)
	v_pk_fma_f32 v[74:75], v[98:99], v[118:119], v[74:75]
	v_cndmask_b32_e64 v77, v85, v77, s[8:9]
	v_mul_f32_e32 v78, 0xbfb8aa3b, v75
	v_exp_f32_e32 v78, v78
	v_pk_mul_f32 v[76:77], v[120:121], v[76:77]
	v_cndmask_b32_e64 v72, v72, v80, s[6:7]
	v_cndmask_b32_e64 v73, v73, v81, s[6:7]
	v_pk_fma_f32 v[72:73], v[112:113], v[72:73], v[76:77]
	v_add_f32_e32 v76, 1.0, v78
	v_mul_f32_e32 v77, 0xbfb8aa3b, v74
	v_rcp_f32_e32 v76, v76
	v_exp_f32_e32 v77, v77
	v_pk_fma_f32 v[72:73], v[96:97], v[116:117], v[72:73]
	v_cndmask_b32_e64 v142, v102, v90, s[8:9]
	v_mul_f32_e32 v75, v75, v76
	v_add_f32_e32 v76, 1.0, v77
	v_mul_f32_e32 v77, 0xbfb8aa3b, v73
	v_mul_f32_e32 v78, 0xbfb8aa3b, v72
	v_rcp_f32_e32 v76, v76
	v_exp_f32_e32 v77, v77
	v_exp_f32_e32 v78, v78
	v_cndmask_b32_e64 v143, v138, v92, s[8:9]
	v_mul_f32_e32 v74, v74, v76
	v_add_f32_e32 v76, 1.0, v77
	v_add_f32_e32 v77, 1.0, v78
	v_rcp_f32_e32 v76, v76
	v_rcp_f32_e32 v77, v77
	v_cndmask_b32_e64 v94, v140, v94, s[8:9]
	v_cndmask_b32_e64 v95, v141, v95, s[8:9]
	v_cndmask_b32_e64 v88, v88, v100, s[6:7]
	v_cndmask_b32_e64 v89, v89, v101, s[6:7]
	v_cndmask_b32_e64 v90, v91, v103, s[6:7]
	v_cndmask_b32_e64 v91, v93, v139, s[6:7]
	v_pk_mul_f32 v[92:93], v[124:125], v[142:143]
	v_pk_mul_f32 v[94:95], v[126:127], v[94:95]
	v_pk_fma_f32 v[88:89], v[128:129], v[88:89], v[92:93]
	v_pk_fma_f32 v[90:91], v[130:131], v[90:91], v[94:95]
	s_waitcnt vmcnt(0)
	v_pk_fma_f32 v[88:89], v[104:105], v[132:133], v[88:89]
	v_pk_fma_f32 v[90:91], v[106:107], v[134:135], v[90:91]
	v_mul_f32_e32 v73, v73, v76
	v_mul_f32_e32 v72, v72, v77
	v_mul_f32_e32 v75, v75, v91
	v_mul_f32_e32 v74, v74, v90
	v_mul_f32_e32 v73, v73, v89
	v_mul_f32_e32 v72, v72, v88
	v_cvt_pk_bf16_f32 v72, v72, v73
	v_cvt_pk_bf16_f32 v73, v74, v75
	v_mov_b64_e32 v[74:75], s[30:31]
	v_mad_i64_i32 v[74:75], s[70:71], v137, s67, v[74:75]
	v_lshl_add_u64 v[74:75], v[192:193], 1, v[74:75]
	global_store_dwordx2 v[74:75], v[72:73], off

.LBB0_710:
	v_mov_b32_e32 v199, v198
	v_mov_b32_e32 v104, v198
	v_mov_b32_e32 v105, v198
	v_pk_fma_f32 v[62:63], v[62:63], v[104:105], v[46:47]
	v_pk_fma_f32 v[60:61], v[60:61], v[198:199], v[44:45]
	v_pk_fma_f32 v[58:59], v[58:59], v[104:105], v[42:43]
	v_pk_fma_f32 v[56:57], v[56:57], v[198:199], v[40:41]
	s_waitcnt vmcnt(7)
	s_nop 1
	v_mov_b32_dpp v104, v60 row_ror:1 row_mask:0xf bank_mask:0xf
	v_mov_b32_dpp v112, v60 row_ror:2 row_mask:0xf bank_mask:0xf
	v_mov_b32_dpp v105, v61 row_ror:1 row_mask:0xf bank_mask:0xf
	v_mov_b32_dpp v113, v61 row_ror:2 row_mask:0xf bank_mask:0xf
	v_mov_b32_dpp v106, v62 row_ror:1 row_mask:0xf bank_mask:0xf
	v_mov_b32_dpp v114, v62 row_ror:2 row_mask:0xf bank_mask:0xf
	v_mov_b32_dpp v107, v63 row_ror:1 row_mask:0xf bank_mask:0xf
	v_mov_b32_dpp v115, v63 row_ror:2 row_mask:0xf bank_mask:0xf
	v_mov_b32_dpp v116, v56 row_ror:1 row_mask:0xf bank_mask:0xf
	v_mov_b32_dpp v118, v56 row_ror:2 row_mask:0xf bank_mask:0xf
	v_mov_b32_dpp v117, v57 row_ror:1 row_mask:0xf bank_mask:0xf
	v_mov_b32_dpp v120, v57 row_ror:2 row_mask:0xf bank_mask:0xf
	v_mov_b32_dpp v119, v58 row_ror:1 row_mask:0xf bank_mask:0xf
	v_mov_b32_dpp v122, v58 row_ror:2 row_mask:0xf bank_mask:0xf
	v_mov_b32_dpp v121, v59 row_ror:1 row_mask:0xf bank_mask:0xf
	v_mov_b32_dpp v123, v59 row_ror:2 row_mask:0xf bank_mask:0xf
	s_and_saveexec_b64 s[46:47], s[0:1]
	s_cbranch_execz .LBB0_712
	v_cndmask_b32_e64 v130, v130, v122, s[8:9]
	v_cndmask_b32_e64 v131, v131, v123, s[8:9]
	v_cndmask_b32_e64 v102, v119, v102, s[6:7]
	v_cndmask_b32_e64 v103, v121, v103, s[6:7]
	s_waitcnt vmcnt(4)
	v_pk_mul_f32 v[130:131], v[86:87], v[130:131]
	v_cndmask_b32_e64 v98, v106, v98, s[6:7]
	s_waitcnt vmcnt(2)
	v_pk_fma_f32 v[102:103], v[90:91], v[102:103], v[130:131]
	v_cndmask_b32_e64 v99, v107, v99, s[6:7]
	s_waitcnt vmcnt(0)
	v_pk_fma_f32 v[58:59], v[58:59], v[94:95], v[102:103]
	v_cndmask_b32_e64 v102, v126, v114, s[8:9]
	v_cndmask_b32_e64 v103, v127, v115, s[8:9]
	v_pk_mul_f32 v[102:103], v[78:79], v[102:103]
	v_cndmask_b32_e64 v128, v128, v118, s[8:9]
	v_pk_fma_f32 v[98:99], v[74:75], v[98:99], v[102:103]
	v_cndmask_b32_e64 v129, v129, v120, s[8:9]
	v_pk_fma_f32 v[62:63], v[62:63], v[82:83], v[98:99]
	v_cndmask_b32_e64 v100, v116, v100, s[6:7]
	v_mul_f32_e32 v98, 0xbfb8aa3b, v63
	v_exp_f32_e32 v98, v98
	v_cndmask_b32_e64 v101, v117, v101, s[6:7]
	v_pk_mul_f32 v[128:129], v[84:85], v[128:129]
	v_mul_f32_e32 v99, 0xbfb8aa3b, v62
	v_add_f32_e32 v98, 1.0, v98
	v_pk_fma_f32 v[100:101], v[88:89], v[100:101], v[128:129]
	v_rcp_f32_e32 v98, v98
	v_pk_fma_f32 v[56:57], v[56:57], v[92:93], v[100:101]
	v_cndmask_b32_e64 v100, v124, v112, s[8:9]
	v_cndmask_b32_e64 v101, v125, v113, s[8:9]
	v_exp_f32_e32 v99, v99
	v_pk_mul_f32 v[100:101], v[76:77], v[100:101]
	v_cndmask_b32_e64 v96, v104, v96, s[6:7]
	v_cndmask_b32_e64 v97, v105, v97, s[6:7]
	v_pk_fma_f32 v[96:97], v[72:73], v[96:97], v[100:101]
	v_mul_f32_e32 v63, v63, v98
	v_pk_fma_f32 v[60:61], v[60:61], v[80:81], v[96:97]
	v_mul_f32_e32 v59, v63, v59
	v_add_f32_e32 v63, 1.0, v99
	v_mul_f32_e32 v96, 0xbfb8aa3b, v61
	v_mul_f32_e32 v97, 0xbfb8aa3b, v60
	v_rcp_f32_e32 v63, v63
	v_exp_f32_e32 v96, v96
	v_exp_f32_e32 v97, v97
	v_mul_f32_e32 v62, v62, v63
	v_add_f32_e32 v63, 1.0, v96
	v_add_f32_e32 v96, 1.0, v97
	v_rcp_f32_e32 v63, v63
	v_rcp_f32_e32 v96, v96
	v_mul_f32_e32 v58, v62, v58
	v_mul_f32_e32 v61, v61, v63
	v_mul_f32_e32 v60, v60, v96
	v_mul_f32_e32 v57, v61, v57
	v_mul_f32_e32 v56, v60, v56
	v_cvt_pk_bf16_f32 v56, v56, v57
	v_cvt_pk_bf16_f32 v57, v58, v59
	v_mov_b64_e32 v[58:59], s[30:31]
	v_mad_i64_i32 v[58:59], s[0:1], v194, s67, v[58:59]
	v_lshl_add_u64 v[58:59], v[192:193], 1, v[58:59]
	global_store_dwordx2 v[58:59], v[56:57], off offset:8
.LBB0_712:
	s_or_b64 exec, exec, s[46:47]
	v_mov_b32_e32 v153, v152
	v_mov_b32_e32 v56, v152
	v_mov_b32_e32 v57, v152
	v_pk_fma_f32 v[54:55], v[54:55], v[56:57], v[46:47]
	v_pk_fma_f32 v[52:53], v[52:53], v[152:153], v[44:45]
	v_pk_fma_f32 v[50:51], v[50:51], v[56:57], v[42:43]
	v_pk_fma_f32 v[48:49], v[48:49], v[152:153], v[40:41]
	s_nop 1
	v_mov_b32_dpp v56, v52 row_ror:1 row_mask:0xf bank_mask:0xf
	v_mov_b32_dpp v60, v52 row_ror:2 row_mask:0xf bank_mask:0xf
	v_mov_b32_dpp v57, v53 row_ror:1 row_mask:0xf bank_mask:0xf
	v_mov_b32_dpp v61, v53 row_ror:2 row_mask:0xf bank_mask:0xf
	v_mov_b32_dpp v58, v54 row_ror:1 row_mask:0xf bank_mask:0xf
	v_mov_b32_dpp v62, v54 row_ror:2 row_mask:0xf bank_mask:0xf
	v_mov_b32_dpp v59, v55 row_ror:1 row_mask:0xf bank_mask:0xf
	v_mov_b32_dpp v63, v55 row_ror:2 row_mask:0xf bank_mask:0xf
	v_mov_b32_dpp v96, v48 row_ror:1 row_mask:0xf bank_mask:0xf
	v_mov_b32_dpp v98, v48 row_ror:2 row_mask:0xf bank_mask:0xf
	v_mov_b32_dpp v97, v49 row_ror:1 row_mask:0xf bank_mask:0xf
	v_mov_b32_dpp v100, v49 row_ror:2 row_mask:0xf bank_mask:0xf
	v_mov_b32_dpp v99, v50 row_ror:1 row_mask:0xf bank_mask:0xf
	v_mov_b32_dpp v102, v50 row_ror:2 row_mask:0xf bank_mask:0xf
	v_mov_b32_dpp v101, v51 row_ror:1 row_mask:0xf bank_mask:0xf
	v_mov_b32_dpp v103, v51 row_ror:2 row_mask:0xf bank_mask:0xf
	s_and_saveexec_b64 s[0:1], s[16:17]
	s_cbranch_execz .LBB0_714
	v_cndmask_b32_e64 v114, v114, v62, s[8:9]
	v_cndmask_b32_e64 v115, v115, v63, s[8:9]
	s_waitcnt vmcnt(5)
	v_pk_mul_f32 v[114:115], v[78:79], v[114:115]
	v_cndmask_b32_e64 v106, v58, v106, s[6:7]
	v_cndmask_b32_e64 v107, v59, v107, s[6:7]
	s_waitcnt vmcnt(3)
	v_pk_fma_f32 v[106:107], v[74:75], v[106:107], v[114:115]
	v_cndmask_b32_e64 v122, v122, v102, s[8:9]
	s_waitcnt vmcnt(1)
	v_pk_fma_f32 v[54:55], v[54:55], v[82:83], v[106:107]
	v_cndmask_b32_e64 v123, v123, v103, s[8:9]
	v_mul_f32_e32 v106, 0xbfb8aa3b, v55
	v_exp_f32_e32 v106, v106
	v_mul_f32_e32 v107, 0xbfb8aa3b, v54
	v_cndmask_b32_e64 v112, v112, v60, s[8:9]
	v_cndmask_b32_e64 v113, v113, v61, s[8:9]
	v_add_f32_e32 v106, 1.0, v106
	v_rcp_f32_e32 v106, v106
	v_exp_f32_e32 v107, v107
	v_cndmask_b32_e64 v124, v118, v98, s[8:9]
	v_cndmask_b32_e64 v118, v99, v119, s[6:7]
	v_cndmask_b32_e64 v119, v101, v121, s[6:7]
	v_pk_mul_f32 v[122:123], v[86:87], v[122:123]
	v_pk_mul_f32 v[112:113], v[76:77], v[112:113]
	v_cndmask_b32_e64 v104, v56, v104, s[6:7]
	v_cndmask_b32_e64 v105, v57, v105, s[6:7]
	v_pk_fma_f32 v[118:119], v[90:91], v[118:119], v[122:123]
	v_pk_fma_f32 v[104:105], v[72:73], v[104:105], v[112:113]
	s_waitcnt vmcnt(0)
	v_pk_fma_f32 v[50:51], v[50:51], v[94:95], v[118:119]
	v_pk_fma_f32 v[52:53], v[52:53], v[80:81], v[104:105]
	v_mul_f32_e32 v55, v55, v106
	v_mul_f32_e32 v51, v55, v51
	v_add_f32_e32 v55, 1.0, v107
	v_mul_f32_e32 v104, 0xbfb8aa3b, v53
	v_mul_f32_e32 v105, 0xbfb8aa3b, v52
	v_rcp_f32_e32 v55, v55
	v_exp_f32_e32 v104, v104
	v_exp_f32_e32 v105, v105
	v_cndmask_b32_e64 v125, v120, v100, s[8:9]
	v_mul_f32_e32 v54, v54, v55
	v_add_f32_e32 v55, 1.0, v104
	v_add_f32_e32 v104, 1.0, v105
	v_rcp_f32_e32 v55, v55
	v_rcp_f32_e32 v104, v104
	v_cndmask_b32_e64 v116, v96, v116, s[6:7]
	v_cndmask_b32_e64 v117, v97, v117, s[6:7]
	v_pk_mul_f32 v[120:121], v[84:85], v[124:125]
	v_mul_f32_e32 v53, v53, v55
	v_pk_fma_f32 v[116:117], v[88:89], v[116:117], v[120:121]
	v_mul_f32_e32 v52, v52, v104
	v_pk_fma_f32 v[48:49], v[48:49], v[92:93], v[116:117]
	v_mul_f32_e32 v50, v54, v50
	v_mul_f32_e32 v49, v53, v49
	v_mul_f32_e32 v48, v52, v48
	v_cvt_pk_bf16_f32 v48, v48, v49
	v_cvt_pk_bf16_f32 v49, v50, v51
	v_mov_b64_e32 v[50:51], s[30:31]
	v_mad_i64_i32 v[50:51], s[16:17], v154, s67, v[50:51]
	v_lshl_add_u64 v[50:51], v[192:193], 1, v[50:51]
	global_store_dwordx2 v[50:51], v[48:49], off offset:8
.LBB0_714:
	s_or_b64 exec, exec, s[0:1]
	v_mov_b32_e32 v145, v144
	v_mov_b32_e32 v48, v144
	v_mov_b32_e32 v49, v144
	v_pk_fma_f32 v[34:35], v[34:35], v[48:49], v[46:47]
	v_pk_fma_f32 v[32:33], v[32:33], v[144:145], v[44:45]
	v_pk_fma_f32 v[30:31], v[30:31], v[48:49], v[42:43]
	v_pk_fma_f32 v[28:29], v[28:29], v[144:145], v[40:41]
	s_nop 1
	v_mov_b32_dpp v48, v32 row_ror:1 row_mask:0xf bank_mask:0xf
	v_mov_b32_dpp v52, v32 row_ror:2 row_mask:0xf bank_mask:0xf
	v_mov_b32_dpp v49, v33 row_ror:1 row_mask:0xf bank_mask:0xf
	v_mov_b32_dpp v53, v33 row_ror:2 row_mask:0xf bank_mask:0xf
	v_mov_b32_dpp v50, v34 row_ror:1 row_mask:0xf bank_mask:0xf
	v_mov_b32_dpp v54, v34 row_ror:2 row_mask:0xf bank_mask:0xf
	v_mov_b32_dpp v51, v35 row_ror:1 row_mask:0xf bank_mask:0xf
	v_mov_b32_dpp v55, v35 row_ror:2 row_mask:0xf bank_mask:0xf
	v_mov_b32_dpp v104, v28 row_ror:1 row_mask:0xf bank_mask:0xf
	v_mov_b32_dpp v106, v28 row_ror:2 row_mask:0xf bank_mask:0xf
	v_mov_b32_dpp v105, v29 row_ror:1 row_mask:0xf bank_mask:0xf
	v_mov_b32_dpp v112, v29 row_ror:2 row_mask:0xf bank_mask:0xf
	v_mov_b32_dpp v107, v30 row_ror:1 row_mask:0xf bank_mask:0xf
	v_mov_b32_dpp v114, v30 row_ror:2 row_mask:0xf bank_mask:0xf
	v_mov_b32_dpp v113, v31 row_ror:1 row_mask:0xf bank_mask:0xf
	v_mov_b32_dpp v115, v31 row_ror:2 row_mask:0xf bank_mask:0xf
	s_and_saveexec_b64 s[0:1], s[18:19]
	s_cbranch_execz .LBB0_716
	v_cndmask_b32_e64 v62, v62, v54, s[8:9]
	v_cndmask_b32_e64 v63, v63, v55, s[8:9]
	s_waitcnt vmcnt(5)
	v_pk_mul_f32 v[62:63], v[78:79], v[62:63]
	v_cndmask_b32_e64 v58, v50, v58, s[6:7]
	v_cndmask_b32_e64 v59, v51, v59, s[6:7]
	s_waitcnt vmcnt(3)
	v_pk_fma_f32 v[58:59], v[74:75], v[58:59], v[62:63]
	v_cndmask_b32_e64 v102, v102, v114, s[8:9]
	s_waitcnt vmcnt(1)
	v_pk_fma_f32 v[34:35], v[34:35], v[82:83], v[58:59]
	v_cndmask_b32_e64 v103, v103, v115, s[8:9]
	v_mul_f32_e32 v58, 0xbfb8aa3b, v35
	v_exp_f32_e32 v58, v58
	v_mul_f32_e32 v59, 0xbfb8aa3b, v34
	v_cndmask_b32_e64 v60, v60, v52, s[8:9]
	v_cndmask_b32_e64 v61, v61, v53, s[8:9]
	v_add_f32_e32 v58, 1.0, v58
	v_rcp_f32_e32 v58, v58
	v_exp_f32_e32 v59, v59
	v_cndmask_b32_e64 v116, v98, v106, s[8:9]
	v_cndmask_b32_e64 v98, v107, v99, s[6:7]
	v_cndmask_b32_e64 v99, v113, v101, s[6:7]
	v_pk_mul_f32 v[102:103], v[86:87], v[102:103]
	v_pk_mul_f32 v[60:61], v[76:77], v[60:61]
	v_cndmask_b32_e64 v56, v48, v56, s[6:7]
	v_cndmask_b32_e64 v57, v49, v57, s[6:7]
	v_pk_fma_f32 v[98:99], v[90:91], v[98:99], v[102:103]
	v_pk_fma_f32 v[56:57], v[72:73], v[56:57], v[60:61]
	s_waitcnt vmcnt(0)
	v_pk_fma_f32 v[30:31], v[30:31], v[94:95], v[98:99]
	v_pk_fma_f32 v[32:33], v[32:33], v[80:81], v[56:57]
	v_mul_f32_e32 v35, v35, v58
	v_mul_f32_e32 v31, v35, v31
	v_add_f32_e32 v35, 1.0, v59
	v_mul_f32_e32 v56, 0xbfb8aa3b, v33
	v_mul_f32_e32 v57, 0xbfb8aa3b, v32
	v_rcp_f32_e32 v35, v35
	v_exp_f32_e32 v56, v56
	v_exp_f32_e32 v57, v57
	v_cndmask_b32_e64 v117, v100, v112, s[8:9]
	v_mul_f32_e32 v34, v34, v35
	v_add_f32_e32 v35, 1.0, v56
	v_add_f32_e32 v56, 1.0, v57
	v_rcp_f32_e32 v35, v35
	v_rcp_f32_e32 v56, v56
	v_cndmask_b32_e64 v96, v104, v96, s[6:7]
	v_cndmask_b32_e64 v97, v105, v97, s[6:7]
	v_pk_mul_f32 v[100:101], v[84:85], v[116:117]
	v_mul_f32_e32 v33, v33, v35
	v_pk_fma_f32 v[96:97], v[88:89], v[96:97], v[100:101]
	v_mul_f32_e32 v32, v32, v56
	v_pk_fma_f32 v[28:29], v[28:29], v[92:93], v[96:97]
	v_mul_f32_e32 v30, v34, v30
	v_mul_f32_e32 v29, v33, v29
	v_mul_f32_e32 v28, v32, v28
	v_cvt_pk_bf16_f32 v28, v28, v29
	v_cvt_pk_bf16_f32 v29, v30, v31
	v_mov_b64_e32 v[30:31], s[30:31]
	v_mad_i64_i32 v[30:31], s[16:17], v147, s67, v[30:31]
	v_lshl_add_u64 v[30:31], v[192:193], 1, v[30:31]
	global_store_dwordx2 v[30:31], v[28:29], off offset:8
.LBB0_716:
	s_or_b64 exec, exec, s[0:1]
	s_nop 1
	v_mov_b32_dpp v28, v64 row_ror:1 row_mask:0xf bank_mask:0xf
	v_mov_b32_dpp v32, v64 row_ror:2 row_mask:0xf bank_mask:0xf
	v_mov_b32_dpp v29, v65 row_ror:1 row_mask:0xf bank_mask:0xf
	v_mov_b32_dpp v33, v65 row_ror:2 row_mask:0xf bank_mask:0xf
	v_mov_b32_dpp v30, v66 row_ror:1 row_mask:0xf bank_mask:0xf
	v_mov_b32_dpp v34, v66 row_ror:2 row_mask:0xf bank_mask:0xf
	v_mov_b32_dpp v31, v67 row_ror:1 row_mask:0xf bank_mask:0xf
	v_mov_b32_dpp v35, v67 row_ror:2 row_mask:0xf bank_mask:0xf
	v_mov_b32_dpp v56, v68 row_ror:1 row_mask:0xf bank_mask:0xf
	v_mov_b32_dpp v58, v68 row_ror:2 row_mask:0xf bank_mask:0xf
	v_mov_b32_dpp v57, v69 row_ror:1 row_mask:0xf bank_mask:0xf
	v_mov_b32_dpp v60, v69 row_ror:2 row_mask:0xf bank_mask:0xf
	v_mov_b32_dpp v59, v70 row_ror:1 row_mask:0xf bank_mask:0xf
	v_mov_b32_dpp v62, v70 row_ror:2 row_mask:0xf bank_mask:0xf
	v_mov_b32_dpp v61, v71 row_ror:1 row_mask:0xf bank_mask:0xf
	v_mov_b32_dpp v63, v71 row_ror:2 row_mask:0xf bank_mask:0xf
	s_and_saveexec_b64 s[0:1], s[20:21]
	s_cbranch_execz .LBB0_718
	v_cndmask_b32_e64 v34, v54, v34, s[8:9]
	v_cndmask_b32_e64 v35, v55, v35, s[8:9]
	s_waitcnt vmcnt(5)
	v_pk_mul_f32 v[34:35], v[78:79], v[34:35]
	v_cndmask_b32_e64 v30, v30, v50, s[6:7]
	v_cndmask_b32_e64 v31, v31, v51, s[6:7]
	s_waitcnt vmcnt(3)
	v_pk_fma_f32 v[30:31], v[74:75], v[30:31], v[34:35]
	v_cndmask_b32_e64 v32, v52, v32, s[8:9]
	s_waitcnt vmcnt(1)
	v_pk_fma_f32 v[30:31], v[66:67], v[82:83], v[30:31]
	v_cndmask_b32_e64 v33, v53, v33, s[8:9]
	v_mul_f32_e32 v34, 0xbfb8aa3b, v31
	v_exp_f32_e32 v34, v34
	v_pk_mul_f32 v[32:33], v[76:77], v[32:33]
	v_cndmask_b32_e64 v28, v28, v48, s[6:7]
	v_cndmask_b32_e64 v29, v29, v49, s[6:7]
	v_pk_fma_f32 v[28:29], v[72:73], v[28:29], v[32:33]
	v_add_f32_e32 v32, 1.0, v34
	v_mul_f32_e32 v33, 0xbfb8aa3b, v30
	v_rcp_f32_e32 v32, v32
	v_exp_f32_e32 v33, v33
	v_pk_fma_f32 v[28:29], v[64:65], v[80:81], v[28:29]
	v_cndmask_b32_e64 v96, v106, v58, s[8:9]
	v_mul_f32_e32 v31, v31, v32
	v_add_f32_e32 v32, 1.0, v33
	v_mul_f32_e32 v33, 0xbfb8aa3b, v29
	v_mul_f32_e32 v34, 0xbfb8aa3b, v28
	v_rcp_f32_e32 v32, v32
	v_exp_f32_e32 v33, v33
	v_exp_f32_e32 v34, v34
	v_cndmask_b32_e64 v97, v112, v60, s[8:9]
	v_mul_f32_e32 v30, v30, v32
	v_add_f32_e32 v32, 1.0, v33
	v_add_f32_e32 v33, 1.0, v34
	v_rcp_f32_e32 v32, v32
	v_rcp_f32_e32 v33, v33
	v_cndmask_b32_e64 v62, v114, v62, s[8:9]
	v_cndmask_b32_e64 v63, v115, v63, s[8:9]
	v_cndmask_b32_e64 v56, v56, v104, s[6:7]
	v_cndmask_b32_e64 v57, v57, v105, s[6:7]
	v_cndmask_b32_e64 v58, v59, v107, s[6:7]
	v_cndmask_b32_e64 v59, v61, v113, s[6:7]
	v_pk_mul_f32 v[60:61], v[84:85], v[96:97]
	v_pk_mul_f32 v[62:63], v[86:87], v[62:63]
	v_pk_fma_f32 v[56:57], v[88:89], v[56:57], v[60:61]
	v_pk_fma_f32 v[58:59], v[90:91], v[58:59], v[62:63]
	s_waitcnt vmcnt(0)
	v_pk_fma_f32 v[56:57], v[68:69], v[92:93], v[56:57]
	v_pk_fma_f32 v[58:59], v[70:71], v[94:95], v[58:59]
	v_mul_f32_e32 v29, v29, v32
	v_mul_f32_e32 v28, v28, v33
	v_mul_f32_e32 v31, v31, v59
	v_mul_f32_e32 v30, v30, v58
	v_mul_f32_e32 v29, v29, v57
	v_mul_f32_e32 v28, v28, v56
	v_cvt_pk_bf16_f32 v28, v28, v29
	v_cvt_pk_bf16_f32 v29, v30, v31
	v_mov_b64_e32 v[30:31], s[30:31]
	v_mad_i64_i32 v[30:31], s[16:17], v109, s67, v[30:31]
	v_lshl_add_u64 v[30:31], v[192:193], 1, v[30:31]
	global_store_dwordx2 v[30:31], v[28:29], off offset:8
.LBB0_718:
	s_or_b64 exec, exec, s[0:1]
	v_mov_b32_e32 v109, v108
	v_mov_b32_e32 v28, v108
	v_mov_b32_e32 v29, v108
	v_pk_fma_f32 v[22:23], v[22:23], v[28:29], v[46:47]
	v_pk_fma_f32 v[20:21], v[20:21], v[108:109], v[44:45]
	v_pk_fma_f32 v[18:19], v[18:19], v[28:29], v[42:43]
	v_pk_fma_f32 v[16:17], v[16:17], v[108:109], v[40:41]
	s_nop 1
	v_mov_b32_dpp v28, v20 row_ror:1 row_mask:0xf bank_mask:0xf
	v_mov_b32_dpp v32, v20 row_ror:2 row_mask:0xf bank_mask:0xf
	v_mov_b32_dpp v29, v21 row_ror:1 row_mask:0xf bank_mask:0xf
	v_mov_b32_dpp v33, v21 row_ror:2 row_mask:0xf bank_mask:0xf
	v_mov_b32_dpp v30, v22 row_ror:1 row_mask:0xf bank_mask:0xf
	v_mov_b32_dpp v34, v22 row_ror:2 row_mask:0xf bank_mask:0xf
	v_mov_b32_dpp v31, v23 row_ror:1 row_mask:0xf bank_mask:0xf
	v_mov_b32_dpp v35, v23 row_ror:2 row_mask:0xf bank_mask:0xf
	v_mov_b32_dpp v48, v16 row_ror:1 row_mask:0xf bank_mask:0xf
	v_mov_b32_dpp v50, v16 row_ror:2 row_mask:0xf bank_mask:0xf
	v_mov_b32_dpp v49, v17 row_ror:1 row_mask:0xf bank_mask:0xf
	v_mov_b32_dpp v52, v17 row_ror:2 row_mask:0xf bank_mask:0xf
	v_mov_b32_dpp v51, v18 row_ror:1 row_mask:0xf bank_mask:0xf
	v_mov_b32_dpp v54, v18 row_ror:2 row_mask:0xf bank_mask:0xf
	v_mov_b32_dpp v53, v19 row_ror:1 row_mask:0xf bank_mask:0xf
	v_mov_b32_dpp v55, v19 row_ror:2 row_mask:0xf bank_mask:0xf
	s_and_saveexec_b64 s[0:1], s[22:23]
	s_cbranch_execz .LBB0_720
	ds_read_b128 v[56:59], v149 offset:304
	ds_read_b128 v[60:63], v149 offset:48
	ds_read_b128 v[64:67], v149 offset:16
	ds_read_b128 v[68:71], v149 offset:272
	s_waitcnt lgkmcnt(2)
	v_cndmask_b32_e64 v63, v59, v63, s[6:7]
	v_cndmask_b32_e64 v62, v58, v62, s[6:7]
	v_cndmask_b32_e64 v62, v62, v54, s[8:9]
	v_cndmask_b32_e64 v63, v63, v55, s[8:9]
	v_cndmask_b32_e64 v58, v51, v58, s[6:7]
	v_cndmask_b32_e64 v59, v53, v59, s[6:7]
	s_waitcnt vmcnt(4)
	v_pk_mul_f32 v[62:63], v[86:87], v[62:63]
	v_cndmask_b32_e64 v61, v57, v61, s[6:7]
	v_cndmask_b32_e64 v60, v56, v60, s[6:7]
	s_waitcnt vmcnt(2)
	v_pk_fma_f32 v[58:59], v[90:91], v[58:59], v[62:63]
	v_cndmask_b32_e64 v60, v60, v50, s[8:9]
	v_cndmask_b32_e64 v61, v61, v52, s[8:9]
	s_waitcnt vmcnt(0)
	v_pk_fma_f32 v[18:19], v[18:19], v[94:95], v[58:59]
	s_waitcnt lgkmcnt(0)
	v_cndmask_b32_e64 v59, v71, v67, s[6:7]
	v_cndmask_b32_e64 v58, v70, v66, s[6:7]
	v_cndmask_b32_e64 v56, v48, v56, s[6:7]
	v_cndmask_b32_e64 v57, v49, v57, s[6:7]
	v_pk_mul_f32 v[60:61], v[84:85], v[60:61]
	v_cndmask_b32_e64 v58, v58, v34, s[8:9]
	v_cndmask_b32_e64 v59, v59, v35, s[8:9]
	v_pk_fma_f32 v[56:57], v[88:89], v[56:57], v[60:61]
	v_pk_mul_f32 v[58:59], v[78:79], v[58:59]
	v_cndmask_b32_e64 v60, v30, v70, s[6:7]
	v_cndmask_b32_e64 v61, v31, v71, s[6:7]
	v_pk_fma_f32 v[58:59], v[74:75], v[60:61], v[58:59]
	v_pk_fma_f32 v[16:17], v[16:17], v[92:93], v[56:57]
	v_pk_fma_f32 v[22:23], v[22:23], v[82:83], v[58:59]
	v_cndmask_b32_e64 v57, v69, v65, s[6:7]
	v_mul_f32_e32 v58, 0xbfb8aa3b, v23
	v_exp_f32_e32 v60, v58
	v_cndmask_b32_e64 v56, v68, v64, s[6:7]
	v_cndmask_b32_e64 v56, v56, v32, s[8:9]
	v_cndmask_b32_e64 v57, v57, v33, s[8:9]
	v_pk_mul_f32 v[56:57], v[76:77], v[56:57]
	v_cndmask_b32_e64 v58, v28, v68, s[6:7]
	v_cndmask_b32_e64 v59, v29, v69, s[6:7]
	v_pk_fma_f32 v[56:57], v[72:73], v[58:59], v[56:57]
	v_add_f32_e32 v58, 1.0, v60
	v_rcp_f32_e32 v58, v58
	v_mul_f32_e32 v59, 0xbfb8aa3b, v22
	v_exp_f32_e32 v59, v59
	v_pk_fma_f32 v[20:21], v[20:21], v[80:81], v[56:57]
	v_mul_f32_e32 v23, v23, v58
	v_mul_f32_e32 v19, v19, v23
	v_add_f32_e32 v23, 1.0, v59
	v_mul_f32_e32 v56, 0xbfb8aa3b, v21
	v_mul_f32_e32 v57, 0xbfb8aa3b, v20
	v_rcp_f32_e32 v23, v23
	v_exp_f32_e32 v56, v56
	v_exp_f32_e32 v57, v57
	v_mul_f32_e32 v22, v22, v23
	v_add_f32_e32 v23, 1.0, v56
	v_add_f32_e32 v56, 1.0, v57
	v_rcp_f32_e32 v23, v23
	v_rcp_f32_e32 v56, v56
	v_mul_f32_e32 v18, v18, v22
	v_mul_f32_e32 v21, v21, v23
	v_mul_f32_e32 v20, v20, v56
	v_mul_f32_e32 v17, v17, v21
	v_mul_f32_e32 v16, v16, v20
	v_cvt_pk_bf16_f32 v16, v16, v17
	v_cvt_pk_bf16_f32 v17, v18, v19
	v_mov_b64_e32 v[18:19], s[30:31]
	v_mad_i64_i32 v[18:19], s[16:17], v111, s67, v[18:19]
	v_lshl_add_u64 v[18:19], v[192:193], 1, v[18:19]
	global_store_dwordx2 v[18:19], v[16:17], off offset:8
.LBB0_720:
	s_or_b64 exec, exec, s[0:1]
	v_mov_b32_e32 v147, v146
	v_mov_b32_e32 v16, v146
	v_mov_b32_e32 v17, v146
	v_pk_fma_f32 v[14:15], v[14:15], v[16:17], v[46:47]
	v_pk_fma_f32 v[12:13], v[12:13], v[146:147], v[44:45]
	v_pk_fma_f32 v[10:11], v[10:11], v[16:17], v[42:43]
	v_pk_fma_f32 v[8:9], v[8:9], v[146:147], v[40:41]
	s_nop 1
	v_mov_b32_dpp v16, v12 row_ror:1 row_mask:0xf bank_mask:0xf
	v_mov_b32_dpp v20, v12 row_ror:2 row_mask:0xf bank_mask:0xf
	v_mov_b32_dpp v17, v13 row_ror:1 row_mask:0xf bank_mask:0xf
	v_mov_b32_dpp v21, v13 row_ror:2 row_mask:0xf bank_mask:0xf
	v_mov_b32_dpp v18, v14 row_ror:1 row_mask:0xf bank_mask:0xf
	v_mov_b32_dpp v22, v14 row_ror:2 row_mask:0xf bank_mask:0xf
	v_mov_b32_dpp v19, v15 row_ror:1 row_mask:0xf bank_mask:0xf
	v_mov_b32_dpp v23, v15 row_ror:2 row_mask:0xf bank_mask:0xf
	v_mov_b32_dpp v56, v8 row_ror:1 row_mask:0xf bank_mask:0xf
	v_mov_b32_dpp v58, v8 row_ror:2 row_mask:0xf bank_mask:0xf
	v_mov_b32_dpp v57, v9 row_ror:1 row_mask:0xf bank_mask:0xf
	v_mov_b32_dpp v60, v9 row_ror:2 row_mask:0xf bank_mask:0xf
	v_mov_b32_dpp v59, v10 row_ror:1 row_mask:0xf bank_mask:0xf
	v_mov_b32_dpp v62, v10 row_ror:2 row_mask:0xf bank_mask:0xf
	v_mov_b32_dpp v61, v11 row_ror:1 row_mask:0xf bank_mask:0xf
	v_mov_b32_dpp v63, v11 row_ror:2 row_mask:0xf bank_mask:0xf
	s_and_saveexec_b64 s[0:1], s[24:25]
	s_cbranch_execz .LBB0_722
	v_cndmask_b32_e64 v34, v34, v22, s[8:9]
	v_cndmask_b32_e64 v35, v35, v23, s[8:9]
	s_waitcnt vmcnt(5)
	v_pk_mul_f32 v[34:35], v[78:79], v[34:35]
	v_cndmask_b32_e64 v30, v18, v30, s[6:7]
	v_cndmask_b32_e64 v31, v19, v31, s[6:7]
	s_waitcnt vmcnt(3)
	v_pk_fma_f32 v[30:31], v[74:75], v[30:31], v[34:35]
	v_cndmask_b32_e64 v54, v54, v62, s[8:9]
	s_waitcnt vmcnt(1)
	v_pk_fma_f32 v[14:15], v[14:15], v[82:83], v[30:31]
	v_cndmask_b32_e64 v55, v55, v63, s[8:9]
	v_mul_f32_e32 v30, 0xbfb8aa3b, v15
	v_exp_f32_e32 v30, v30
	v_mul_f32_e32 v31, 0xbfb8aa3b, v14
	v_cndmask_b32_e64 v32, v32, v20, s[8:9]
	v_cndmask_b32_e64 v33, v33, v21, s[8:9]
	v_add_f32_e32 v30, 1.0, v30
	v_rcp_f32_e32 v30, v30
	v_exp_f32_e32 v31, v31
	v_cndmask_b32_e64 v64, v50, v58, s[8:9]
	v_cndmask_b32_e64 v50, v59, v51, s[6:7]
	v_cndmask_b32_e64 v51, v61, v53, s[6:7]
	v_pk_mul_f32 v[54:55], v[86:87], v[54:55]
	v_pk_mul_f32 v[32:33], v[76:77], v[32:33]
	v_cndmask_b32_e64 v28, v16, v28, s[6:7]
	v_cndmask_b32_e64 v29, v17, v29, s[6:7]
	v_pk_fma_f32 v[50:51], v[90:91], v[50:51], v[54:55]
	v_pk_fma_f32 v[28:29], v[72:73], v[28:29], v[32:33]
	s_waitcnt vmcnt(0)
	v_pk_fma_f32 v[10:11], v[10:11], v[94:95], v[50:51]
	v_pk_fma_f32 v[12:13], v[12:13], v[80:81], v[28:29]
	v_mul_f32_e32 v15, v15, v30
	v_mul_f32_e32 v11, v15, v11
	v_add_f32_e32 v15, 1.0, v31
	v_mul_f32_e32 v28, 0xbfb8aa3b, v13
	v_mul_f32_e32 v29, 0xbfb8aa3b, v12
	v_rcp_f32_e32 v15, v15
	v_exp_f32_e32 v28, v28
	v_exp_f32_e32 v29, v29
	v_cndmask_b32_e64 v65, v52, v60, s[8:9]
	v_mul_f32_e32 v14, v14, v15
	v_add_f32_e32 v15, 1.0, v28
	v_add_f32_e32 v28, 1.0, v29
	v_rcp_f32_e32 v15, v15
	v_rcp_f32_e32 v28, v28
	v_cndmask_b32_e64 v48, v56, v48, s[6:7]
	v_cndmask_b32_e64 v49, v57, v49, s[6:7]
	v_pk_mul_f32 v[52:53], v[84:85], v[64:65]
	v_mul_f32_e32 v13, v13, v15
	v_pk_fma_f32 v[48:49], v[88:89], v[48:49], v[52:53]
	v_mul_f32_e32 v12, v12, v28
	v_pk_fma_f32 v[8:9], v[8:9], v[92:93], v[48:49]
	v_mul_f32_e32 v10, v14, v10
	v_mul_f32_e32 v9, v13, v9
	v_mul_f32_e32 v8, v12, v8
	v_cvt_pk_bf16_f32 v8, v8, v9
	v_cvt_pk_bf16_f32 v9, v10, v11
	v_mov_b64_e32 v[10:11], s[30:31]
	v_mad_i64_i32 v[10:11], s[16:17], v148, s67, v[10:11]
	v_lshl_add_u64 v[10:11], v[192:193], 1, v[10:11]
	global_store_dwordx2 v[10:11], v[8:9], off offset:8
.LBB0_722:
	s_or_b64 exec, exec, s[0:1]
	v_mov_b32_e32 v111, v110
	v_mov_b32_e32 v8, v110
	v_mov_b32_e32 v9, v110
	v_pk_fma_f32 v[6:7], v[6:7], v[8:9], v[46:47]
	v_pk_fma_f32 v[4:5], v[4:5], v[110:111], v[44:45]
	v_pk_fma_f32 v[2:3], v[2:3], v[8:9], v[42:43]
	v_pk_fma_f32 v[0:1], v[0:1], v[110:111], v[40:41]
	s_nop 1
	v_mov_b32_dpp v8, v4 row_ror:1 row_mask:0xf bank_mask:0xf
	v_mov_b32_dpp v12, v4 row_ror:2 row_mask:0xf bank_mask:0xf
	v_mov_b32_dpp v9, v5 row_ror:1 row_mask:0xf bank_mask:0xf
	v_mov_b32_dpp v13, v5 row_ror:2 row_mask:0xf bank_mask:0xf
	v_mov_b32_dpp v10, v6 row_ror:1 row_mask:0xf bank_mask:0xf
	v_mov_b32_dpp v14, v6 row_ror:2 row_mask:0xf bank_mask:0xf
	v_mov_b32_dpp v11, v7 row_ror:1 row_mask:0xf bank_mask:0xf
	v_mov_b32_dpp v15, v7 row_ror:2 row_mask:0xf bank_mask:0xf
	v_mov_b32_dpp v28, v0 row_ror:1 row_mask:0xf bank_mask:0xf
	v_mov_b32_dpp v32, v0 row_ror:2 row_mask:0xf bank_mask:0xf
	v_mov_b32_dpp v29, v1 row_ror:1 row_mask:0xf bank_mask:0xf
	v_mov_b32_dpp v33, v1 row_ror:2 row_mask:0xf bank_mask:0xf
	v_mov_b32_dpp v30, v2 row_ror:1 row_mask:0xf bank_mask:0xf
	v_mov_b32_dpp v34, v2 row_ror:2 row_mask:0xf bank_mask:0xf
	v_mov_b32_dpp v31, v3 row_ror:1 row_mask:0xf bank_mask:0xf
	v_mov_b32_dpp v35, v3 row_ror:2 row_mask:0xf bank_mask:0xf
	s_and_saveexec_b64 s[0:1], s[26:27]
	s_cbranch_execz .LBB0_724
	v_cndmask_b32_e64 v22, v22, v14, s[8:9]
	v_cndmask_b32_e64 v23, v23, v15, s[8:9]
	s_waitcnt vmcnt(5)
	v_pk_mul_f32 v[22:23], v[78:79], v[22:23]
	v_cndmask_b32_e64 v18, v10, v18, s[6:7]
	v_cndmask_b32_e64 v19, v11, v19, s[6:7]
	s_waitcnt vmcnt(3)
	v_pk_fma_f32 v[18:19], v[74:75], v[18:19], v[22:23]
	v_cndmask_b32_e64 v42, v62, v34, s[8:9]
	s_waitcnt vmcnt(1)
	v_pk_fma_f32 v[6:7], v[6:7], v[82:83], v[18:19]
	v_cndmask_b32_e64 v43, v63, v35, s[8:9]
	v_mul_f32_e32 v18, 0xbfb8aa3b, v7
	v_exp_f32_e32 v18, v18
	v_mul_f32_e32 v19, 0xbfb8aa3b, v6
	v_cndmask_b32_e64 v20, v20, v12, s[8:9]
	v_cndmask_b32_e64 v21, v21, v13, s[8:9]
	v_add_f32_e32 v18, 1.0, v18
	v_rcp_f32_e32 v18, v18
	v_exp_f32_e32 v19, v19
	v_cndmask_b32_e64 v46, v30, v59, s[6:7]
	v_cndmask_b32_e64 v47, v31, v61, s[6:7]
	v_pk_mul_f32 v[42:43], v[86:87], v[42:43]
	v_pk_mul_f32 v[20:21], v[76:77], v[20:21]
	v_cndmask_b32_e64 v16, v8, v16, s[6:7]
	v_cndmask_b32_e64 v17, v9, v17, s[6:7]
	v_pk_fma_f32 v[42:43], v[90:91], v[46:47], v[42:43]
	v_pk_fma_f32 v[16:17], v[72:73], v[16:17], v[20:21]
	s_waitcnt vmcnt(0)
	v_pk_fma_f32 v[2:3], v[2:3], v[94:95], v[42:43]
	v_pk_fma_f32 v[4:5], v[4:5], v[80:81], v[16:17]
	v_mul_f32_e32 v7, v7, v18
	v_mul_f32_e32 v3, v7, v3
	v_add_f32_e32 v7, 1.0, v19
	v_mul_f32_e32 v16, 0xbfb8aa3b, v5
	v_mul_f32_e32 v17, 0xbfb8aa3b, v4
	v_rcp_f32_e32 v7, v7
	v_exp_f32_e32 v16, v16
	v_exp_f32_e32 v17, v17
	v_cndmask_b32_e64 v40, v58, v32, s[8:9]
	v_mul_f32_e32 v6, v6, v7
	v_add_f32_e32 v7, 1.0, v16
	v_add_f32_e32 v16, 1.0, v17
	v_rcp_f32_e32 v7, v7
	v_rcp_f32_e32 v16, v16
	v_cndmask_b32_e64 v41, v60, v33, s[8:9]
	v_cndmask_b32_e64 v44, v28, v56, s[6:7]
	v_cndmask_b32_e64 v45, v29, v57, s[6:7]
	v_pk_mul_f32 v[40:41], v[84:85], v[40:41]
	v_mul_f32_e32 v5, v5, v7
	v_pk_fma_f32 v[40:41], v[88:89], v[44:45], v[40:41]
	v_mul_f32_e32 v4, v4, v16
	v_pk_fma_f32 v[0:1], v[0:1], v[92:93], v[40:41]
	v_mul_f32_e32 v2, v6, v2
	v_mul_f32_e32 v1, v5, v1
	v_mul_f32_e32 v0, v4, v0
	v_cvt_pk_bf16_f32 v0, v0, v1
	v_cvt_pk_bf16_f32 v1, v2, v3
	v_mov_b64_e32 v[2:3], s[30:31]
	v_mad_i64_i32 v[2:3], s[16:17], v136, s67, v[2:3]
	v_lshl_add_u64 v[2:3], v[192:193], 1, v[2:3]
	global_store_dwordx2 v[2:3], v[0:1], off offset:8
.LBB0_724:
	s_or_b64 exec, exec, s[0:1]
	s_nop 1
	v_mov_b32_dpp v0, v24 row_ror:1 row_mask:0xf bank_mask:0xf
	v_mov_b32_dpp v4, v24 row_ror:2 row_mask:0xf bank_mask:0xf
	v_mov_b32_dpp v1, v25 row_ror:1 row_mask:0xf bank_mask:0xf
	v_mov_b32_dpp v5, v25 row_ror:2 row_mask:0xf bank_mask:0xf
	v_mov_b32_dpp v2, v26 row_ror:1 row_mask:0xf bank_mask:0xf
	v_mov_b32_dpp v6, v26 row_ror:2 row_mask:0xf bank_mask:0xf
	v_mov_b32_dpp v3, v27 row_ror:1 row_mask:0xf bank_mask:0xf
	v_mov_b32_dpp v7, v27 row_ror:2 row_mask:0xf bank_mask:0xf
	v_mov_b32_dpp v16, v36 row_ror:1 row_mask:0xf bank_mask:0xf
	v_mov_b32_dpp v20, v36 row_ror:2 row_mask:0xf bank_mask:0xf
	v_mov_b32_dpp v17, v37 row_ror:1 row_mask:0xf bank_mask:0xf
	v_mov_b32_dpp v21, v37 row_ror:2 row_mask:0xf bank_mask:0xf
	v_mov_b32_dpp v18, v38 row_ror:1 row_mask:0xf bank_mask:0xf
	v_mov_b32_dpp v22, v38 row_ror:2 row_mask:0xf bank_mask:0xf
	v_mov_b32_dpp v19, v39 row_ror:1 row_mask:0xf bank_mask:0xf
	v_mov_b32_dpp v23, v39 row_ror:2 row_mask:0xf bank_mask:0xf
	s_and_saveexec_b64 s[0:1], s[28:29]
	s_cbranch_execz .LBB0_726
	v_cndmask_b32_e64 v6, v14, v6, s[8:9]
	v_cndmask_b32_e64 v7, v15, v7, s[8:9]
	s_waitcnt vmcnt(5)
	v_pk_mul_f32 v[6:7], v[78:79], v[6:7]
	v_cndmask_b32_e64 v2, v2, v10, s[6:7]
	v_cndmask_b32_e64 v3, v3, v11, s[6:7]
	s_waitcnt vmcnt(3)
	v_pk_fma_f32 v[2:3], v[74:75], v[2:3], v[6:7]
	v_cndmask_b32_e64 v4, v12, v4, s[8:9]
	s_waitcnt vmcnt(1)
	v_pk_fma_f32 v[2:3], v[26:27], v[82:83], v[2:3]
	v_cndmask_b32_e64 v5, v13, v5, s[8:9]
	v_mul_f32_e32 v6, 0xbfb8aa3b, v3
	v_exp_f32_e32 v6, v6
	v_pk_mul_f32 v[4:5], v[76:77], v[4:5]
	v_cndmask_b32_e64 v0, v0, v8, s[6:7]
	v_cndmask_b32_e64 v1, v1, v9, s[6:7]
	v_pk_fma_f32 v[0:1], v[72:73], v[0:1], v[4:5]
	v_add_f32_e32 v4, 1.0, v6
	v_mul_f32_e32 v5, 0xbfb8aa3b, v2
	v_rcp_f32_e32 v4, v4
	v_exp_f32_e32 v5, v5
	v_pk_fma_f32 v[0:1], v[24:25], v[80:81], v[0:1]
	v_cndmask_b32_e64 v20, v32, v20, s[8:9]
	v_mul_f32_e32 v3, v3, v4
	v_add_f32_e32 v4, 1.0, v5
	v_mul_f32_e32 v5, 0xbfb8aa3b, v1
	v_mul_f32_e32 v6, 0xbfb8aa3b, v0
	v_rcp_f32_e32 v4, v4
	v_exp_f32_e32 v5, v5
	v_exp_f32_e32 v6, v6
	v_cndmask_b32_e64 v21, v33, v21, s[8:9]
	v_mul_f32_e32 v2, v2, v4
	v_add_f32_e32 v4, 1.0, v5
	v_add_f32_e32 v5, 1.0, v6
	v_rcp_f32_e32 v4, v4
	v_rcp_f32_e32 v5, v5
	v_cndmask_b32_e64 v22, v34, v22, s[8:9]
	v_cndmask_b32_e64 v23, v35, v23, s[8:9]
	v_pk_mul_f32 v[20:21], v[84:85], v[20:21]
	v_pk_mul_f32 v[22:23], v[86:87], v[22:23]
	v_cndmask_b32_e64 v16, v16, v28, s[6:7]
	v_cndmask_b32_e64 v17, v17, v29, s[6:7]
	v_cndmask_b32_e64 v18, v18, v30, s[6:7]
	v_cndmask_b32_e64 v19, v19, v31, s[6:7]
	v_pk_fma_f32 v[18:19], v[90:91], v[18:19], v[22:23]
	v_pk_fma_f32 v[16:17], v[88:89], v[16:17], v[20:21]
	s_waitcnt vmcnt(0)
	v_pk_fma_f32 v[18:19], v[38:39], v[94:95], v[18:19]
	v_pk_fma_f32 v[16:17], v[36:37], v[92:93], v[16:17]
	v_mul_f32_e32 v1, v1, v4
	v_mul_f32_e32 v0, v0, v5
	v_mul_f32_e32 v3, v3, v19
	v_mul_f32_e32 v2, v2, v18
	v_mul_f32_e32 v1, v1, v17
	v_mul_f32_e32 v0, v0, v16
	v_cvt_pk_bf16_f32 v0, v0, v1
	v_cvt_pk_bf16_f32 v1, v2, v3
	v_mov_b64_e32 v[2:3], s[30:31]
	v_mad_i64_i32 v[2:3], s[16:17], v137, s67, v[2:3]
	v_lshl_add_u64 v[2:3], v[192:193], 1, v[2:3]
	global_store_dwordx2 v[2:3], v[0:1], off offset:8
